# GEMM epilogue de-serialisation: out-GEMM residual add loads issued 16 at a time; gated-merge epilogue (rb phase) prefetches gate and accumulator tiles 4 pieces at a time instead of load-wait per piece
# speedup vs baseline: 1.1267x; 1.0171x over previous
; __device__ __forceinline__ void unpack8(const u32x4 w, float (&f)[8]) { f[0] = bflo(w.x); f[1] = bfhi(w.x); f[2] = bflo(w.y); f[3] = bfhi(w.y); f[4] = bflo(w.z); f[5] = bfhi(w.z); f[6] = bflo(w.w); f[7] = bfhi(w.w); }
; __device__ __forceinline__ u32x4 pack8(const float (&f)[8]) { u32x4 w; w.x = pk2(f[0], f[1]); w.y = pk2(f[2], f[3]); w.z = pk2(f[4], f[5]); w.w = pk2(f[6], f[7]); return w; }
; __device__ __forceinline__ float sigmoidf_(float x) { return __builtin_amdgcn_rcpf(1.0f + __expf(-x)); }
;     __device__ __forceinline__ void operator()(const f32x4 (&acc)[2][2][4][2], const pg8::Unit& u, int wr, int wc, int fr, int fq) const {
;     ...
;                 const size_t row = (size_t)(row0 + ai * 128 + m * 16);
; #pragma unroll
;                 for (int bj = 0; bj < 2; ++bj) {
;                     float gt[8], mv[8], o[8];
;                     unpack8(*(const u32x4*)(Z + row * ZW + goff + col0 + bj * 128), gt);
;                     if (!first) unpack8(*(const u32x4*)(Mb + row * D + col0 + bj * 128), mv);
; #pragma unroll
;                     for (int n = 0; n < 2; ++n)
; #pragma unroll
;                         for (int j = 0; j < 4; ++j) o[4 * n + j] = (first ? 0.f : mv[4 * n + j]) + sigmoidf_(gt[4 * n + j]) * acc[ai][bj][m][n][j];
;                     *(u32x4*)(Mb + row * D + col0 + bj * 128) = pack8(o);
.LBB0_1739:
	v_lshlrev_b32_e32 v18, 16, v8
	v_and_b32_e32 v19, 0xffff0000, v8
	v_lshlrev_b32_e32 v24, 16, v9
	v_and_b32_e32 v25, 0xffff0000, v9
	v_mul_f32_e32 v8, 0xbfb8aa3b, v18
	v_mul_f32_e32 v9, 0xbfb8aa3b, v19
	v_exp_f32_e32 v8, v8
	v_exp_f32_e32 v9, v9
	v_lshlrev_b32_e32 v26, 16, v10
	v_and_b32_e32 v10, 0xffff0000, v10
	v_add_f32_e32 v8, 1.0, v8
	v_add_f32_e32 v9, 1.0, v9
	v_rcp_f32_e32 v8, v8
	v_rcp_f32_e32 v9, v9
	v_lshlrev_b32_e32 v27, 16, v11
	v_and_b32_e32 v11, 0xffff0000, v11
	s_and_b64 vcc, exec, s[2:3]
	v_pk_fma_f32 v[4:5], v[4:5], v[8:9], v[16:17]
	v_mul_f32_e32 v8, 0xbfb8aa3b, v24
	v_mul_f32_e32 v9, 0xbfb8aa3b, v25
	v_exp_f32_e32 v8, v8
	v_exp_f32_e32 v9, v9
	s_mov_b32 s26, s20
	s_mov_b32 s0, s70
	v_add_f32_e32 v8, 1.0, v8
	v_add_f32_e32 v9, 1.0, v9
	v_rcp_f32_e32 v8, v8
	v_rcp_f32_e32 v9, v9
	s_mov_b64 s[30:31], s[24:25]
	s_mov_b64 s[28:29], s[22:23]
	v_pk_fma_f32 v[6:7], v[6:7], v[8:9], v[14:15]
	v_mul_f32_e32 v8, 0xbfb8aa3b, v26
	v_mul_f32_e32 v9, 0xbfb8aa3b, v10
	v_exp_f32_e32 v8, v8
	v_exp_f32_e32 v9, v9
	v_add_f32_e32 v8, 1.0, v8
	v_add_f32_e32 v9, 1.0, v9
	v_rcp_f32_e32 v8, v8
	v_rcp_f32_e32 v9, v9
	s_nop 0
	v_pk_fma_f32 v[8:9], v[0:1], v[8:9], v[12:13]
	v_mul_f32_e32 v0, 0xbfb8aa3b, v27
	v_mul_f32_e32 v1, 0xbfb8aa3b, v11
	v_exp_f32_e32 v0, v0
	v_exp_f32_e32 v1, v1
	v_add_f32_e32 v0, 1.0, v0
	v_add_f32_e32 v1, 1.0, v1
	v_rcp_f32_e32 v0, v0
	v_rcp_f32_e32 v1, v1
	s_nop 0
	v_pk_fma_f32 v[10:11], v[2:3], v[0:1], v[22:23]
	v_cvt_pk_bf16_f32 v0, v4, v5
	v_cvt_pk_bf16_f32 v1, v6, v7
	v_cvt_pk_bf16_f32 v2, v8, v9
	v_cvt_pk_bf16_f32 v3, v10, v11
	global_store_dwordx4 v[20:21], v[0:3], off offset:256
	s_cbranch_vccnz .LBB0_1782

; #define PG8_STAGE(bufoff, gbase, voff) do { _Pragma("unroll") for (int _i = 0; _i < 2; ++_i) \
;         __builtin_amdgcn_global_load_lds((const unsigned*)((const char*)(gbase) + (voff)[_i]), (PG8_LAS unsigned*)(lds + (bufoff) + ldsw + _i * 8192), 16, 0, 0); } while (0)
; #define PG8_LDA(dst, b, h) do { _Pragma("unroll") for (int m = 0; m < 4; ++m) _Pragma("unroll") for (int k = 0; k < 2; ++k) dst[m][k] = *(const PG8_LAS bf16x8*)(lds + PG8_SA(b, h) + aoff + m * 2048 + k * 1024); } while (0)
; #define PG8_LDB(dst, b, h) do { _Pragma("unroll") for (int n = 0; n < 2; ++n) _Pragma("unroll") for (int k = 0; k < 2; ++k) dst[n][k] = *(const PG8_LAS bf16x8*)(lds + PG8_SB(b, h) + boff + n * 2048 + k * 1024); } while (0)
; #define PG8_MMA(ai, bj, At, Bt) do { __builtin_amdgcn_s_setprio(1); _Pragma("unroll") for (int m = 0; m < 4; ++m) _Pragma("unroll") for (int n = 0; n < 2; ++n) _Pragma("unroll") for (int k = 0; k < 2; ++k) \
;         acc[ai][bj][m][n] = __builtin_amdgcn_mfma_f32_16x16x32_bf16(Bt[n][k], At[m][k], acc[ai][bj][m][n], 0, 0, 0); __builtin_amdgcn_s_setprio(0); } while (0)
; #define PG8_WAIT_V(n) asm volatile("s_waitcnt vmcnt(" #n ")" ::: "memory")
; #define PG8_WAIT_L(n) asm volatile("s_waitcnt lgkmcnt(" #n ")" ::: "memory")
; #define PG8_BAR __builtin_amdgcn_s_barrier()
; #define PG8_SCHED __builtin_amdgcn_sched_barrier(0)
; template <class Epi, class Sched>
; __device__ __forceinline__ void gemm_phase(PG8_LAS unsigned char* lds, const Gemm g, const Sched& S, const Epi& E, const int tid_in) {
;     ...
;             PG8_LDB(B0, 0, 0); PG8_SCHED; PG8_LDA(At, 0, 0); PG8_STAGE(PG8_SA(1, 1), a1 + hstepA, voffA);
;             PG8_WAIT_L(8); PG8_BAR; PG8_WAIT_L(0); PG8_MMA(0, 0, At, B0); PG8_BAR; PG8_SCHED;
;             PG8_LDB(B1, 0, 1); PG8_STAGE(PG8_SB(0, 0), b2, voffB);
;             PG8_BAR; PG8_WAIT_L(0); PG8_MMA(0, 1, At, B1); PG8_BAR;
;             PG8_LDA(At, 0, 1); PG8_STAGE(PG8_SA(0, 0), a2, voffA);
;             PG8_BAR; PG8_WAIT_L(0); PG8_MMA(1, 0, At, B0); PG8_BAR; PG8_SCHED;
;             PG8_STAGE(PG8_SB(0, 1), b2 + hstepB, voffB);
;             PG8_WAIT_V(6); PG8_BAR; PG8_MMA(1, 1, At, B1); PG8_BAR;
;             PG8_LDB(B0, 1, 0); PG8_SCHED; PG8_LDA(At, 1, 0); PG8_STAGE(PG8_SA(0, 1), a2 + hstepA, voffA);
;             PG8_WAIT_L(8); PG8_BAR; PG8_WAIT_L(0); PG8_MMA(0, 0, At, B0); PG8_BAR; PG8_SCHED;
.LBB0_1749:
	v_add_u32_e32 v136, s44, v187
	ds_read_b128 v[132:135], v136
	ds_read_b128 v[152:155], v136 offset:1024
	ds_read_b128 v[156:159], v136 offset:2048
	ds_read_b128 v[190:193], v136 offset:3072
	s_add_u32 s4, s28, 0x100
	s_addc_u32 s5, s29, 0
	s_cmp_eq_u32 s74, 12
	s_cselect_b32 s35, s23, s5
	s_cselect_b32 s34, s22, s4
	s_cselect_b32 s31, s21, s73
	s_cselect_b32 s30, s71, s72
	v_lshl_add_u64 v[136:137], s[28:29], 0, v[148:149]
	s_add_i32 m0, s57, 0xc000
	ds_read_b128 v[194:197], v189
	ds_read_b128 v[198:201], v189 offset:1024
	ds_read_b128 v[202:205], v189 offset:2048
	ds_read_b128 v[206:209], v189 offset:3072
	ds_read_b128 v[210:213], v189 offset:4096
	ds_read_b128 v[214:217], v189 offset:5120
	ds_read_b128 v[218:221], v189 offset:6144
	ds_read_b128 v[222:225], v189 offset:7168
	global_load_lds_dwordx4 v[136:137], off
	v_lshl_add_u64 v[136:137], s[28:29], 0, v[150:151]
	s_add_i32 m0, s57, 0xe000
	s_nop 0
	global_load_lds_dwordx4 v[136:137], off
	s_waitcnt lgkmcnt(8)
	s_barrier
	s_waitcnt lgkmcnt(0)
	s_setprio 1
	s_waitcnt lgkmcnt(0)
	v_mfma_f32_16x16x32_bf16 v[128:131], v[132:135], v[194:197], v[128:131]
	v_mfma_f32_16x16x32_bf16 v[124:127], v[156:159], v[194:197], v[124:127]
	v_mfma_f32_16x16x32_bf16 v[112:115], v[132:135], v[202:205], v[112:115]
	v_mfma_f32_16x16x32_bf16 v[108:111], v[156:159], v[202:205], v[108:111]
	v_mfma_f32_16x16x32_bf16 v[96:99], v[132:135], v[210:213], v[96:99]
	v_mfma_f32_16x16x32_bf16 v[92:95], v[156:159], v[210:213], v[92:95]
	v_mfma_f32_16x16x32_bf16 v[80:83], v[132:135], v[218:221], v[80:83]
	v_mfma_f32_16x16x32_bf16 v[76:79], v[156:159], v[218:221], v[76:79]
	v_mfma_f32_16x16x32_bf16 v[128:131], v[152:155], v[198:201], v[128:131]
	v_mfma_f32_16x16x32_bf16 v[124:127], v[190:193], v[198:201], v[124:127]
	v_mfma_f32_16x16x32_bf16 v[112:115], v[152:155], v[206:209], v[112:115]
	v_mfma_f32_16x16x32_bf16 v[108:111], v[190:193], v[206:209], v[108:111]
	v_mfma_f32_16x16x32_bf16 v[96:99], v[152:155], v[214:217], v[96:99]
	v_mfma_f32_16x16x32_bf16 v[92:95], v[190:193], v[214:217], v[92:95]
	v_mfma_f32_16x16x32_bf16 v[80:83], v[152:155], v[222:225], v[80:83]
	v_mfma_f32_16x16x32_bf16 v[76:79], v[190:193], v[222:225], v[76:79]
	s_setprio 0
	s_barrier
	v_add_u32_e32 v136, s45, v187
	s_mov_b32 m0, s27
	ds_read_b128 v[226:229], v136
	ds_read_b128 v[230:233], v136 offset:1024
	ds_read_b128 v[234:237], v136 offset:2048
	ds_read_b128 v[238:241], v136 offset:3072
	v_lshl_add_u64 v[136:137], s[30:31], 0, v[30:31]
	global_load_lds_dwordx4 v[136:137], off
	v_lshl_add_u64 v[138:139], s[30:31], 0, v[146:147]
	s_mov_b32 m0, s56
	s_nop 0
	global_load_lds_dwordx4 v[138:139], off
	s_barrier
	s_waitcnt lgkmcnt(0)
	s_setprio 1
	s_waitcnt lgkmcnt(0)
	v_mfma_f32_16x16x32_bf16 v[120:123], v[226:229], v[194:197], v[120:123]
	v_mfma_f32_16x16x32_bf16 v[116:119], v[234:237], v[194:197], v[116:119]
	v_mfma_f32_16x16x32_bf16 v[104:107], v[226:229], v[202:205], v[104:107]
	v_mfma_f32_16x16x32_bf16 v[100:103], v[234:237], v[202:205], v[100:103]
	v_mfma_f32_16x16x32_bf16 v[88:91], v[226:229], v[210:213], v[88:91]
	v_mfma_f32_16x16x32_bf16 v[84:87], v[234:237], v[210:213], v[84:87]
	v_mfma_f32_16x16x32_bf16 v[72:75], v[226:229], v[218:221], v[72:75]
	v_mfma_f32_16x16x32_bf16 v[68:71], v[234:237], v[218:221], v[68:71]
	v_mfma_f32_16x16x32_bf16 v[120:123], v[230:233], v[198:201], v[120:123]
	v_mfma_f32_16x16x32_bf16 v[116:119], v[238:241], v[198:201], v[116:119]
	v_mfma_f32_16x16x32_bf16 v[104:107], v[230:233], v[206:209], v[104:107]
	v_mfma_f32_16x16x32_bf16 v[100:103], v[238:241], v[206:209], v[100:103]
	v_mfma_f32_16x16x32_bf16 v[88:91], v[230:233], v[214:217], v[88:91]
	v_mfma_f32_16x16x32_bf16 v[84:87], v[238:241], v[214:217], v[84:87]
	v_mfma_f32_16x16x32_bf16 v[72:75], v[230:233], v[222:225], v[72:75]
	v_mfma_f32_16x16x32_bf16 v[68:71], v[238:241], v[222:225], v[68:71]
	s_setprio 0
	s_mov_b32 m0, s57
	v_lshl_add_u64 v[160:161], s[34:35], 0, v[28:29]
	s_barrier
	ds_read_b128 v[194:197], v189 offset:16384
	ds_read_b128 v[198:201], v189 offset:17408
	ds_read_b128 v[202:205], v189 offset:18432
	ds_read_b128 v[206:209], v189 offset:19456
	ds_read_b128 v[210:213], v189 offset:20480
	ds_read_b128 v[214:217], v189 offset:21504
	ds_read_b128 v[218:221], v189 offset:22528
	ds_read_b128 v[222:225], v189 offset:23552
	global_load_lds_dwordx4 v[160:161], off
	v_lshl_add_u64 v[242:243], s[34:35], 0, v[144:145]
	s_mov_b32 m0, s58
	s_nop 0
	global_load_lds_dwordx4 v[242:243], off
	s_barrier
	s_waitcnt lgkmcnt(0)
	s_setprio 1
	s_waitcnt lgkmcnt(0)
	v_mfma_f32_16x16x32_bf16 v[64:67], v[132:135], v[194:197], v[64:67]
	v_mfma_f32_16x16x32_bf16 v[60:63], v[156:159], v[194:197], v[60:63]
	v_mfma_f32_16x16x32_bf16 v[48:51], v[132:135], v[202:205], v[48:51]
	v_mfma_f32_16x16x32_bf16 v[44:47], v[156:159], v[202:205], v[44:47]
	v_mfma_f32_16x16x32_bf16 v[32:35], v[132:135], v[210:213], v[32:35]
	v_mfma_f32_16x16x32_bf16 v[24:27], v[156:159], v[210:213], v[24:27]
	v_mfma_f32_16x16x32_bf16 v[12:15], v[132:135], v[218:221], v[12:15]
	v_mfma_f32_16x16x32_bf16 v[8:11], v[156:159], v[218:221], v[8:11]
	v_mfma_f32_16x16x32_bf16 v[64:67], v[152:155], v[198:201], v[64:67]
	v_mfma_f32_16x16x32_bf16 v[60:63], v[190:193], v[198:201], v[60:63]
	v_mfma_f32_16x16x32_bf16 v[48:51], v[152:155], v[206:209], v[48:51]
	v_mfma_f32_16x16x32_bf16 v[44:47], v[190:193], v[206:209], v[44:47]
	v_mfma_f32_16x16x32_bf16 v[32:35], v[152:155], v[214:217], v[32:35]
	v_mfma_f32_16x16x32_bf16 v[24:27], v[190:193], v[214:217], v[24:27]
	v_mfma_f32_16x16x32_bf16 v[12:15], v[152:155], v[222:225], v[12:15]
	v_mfma_f32_16x16x32_bf16 v[8:11], v[190:193], v[222:225], v[8:11]
	s_setprio 0
	s_barrier
; #define PG8_STAGE(bufoff, gbase, voff) do { _Pragma("unroll") for (int _i = 0; _i < 2; ++_i) \
;         __builtin_amdgcn_global_load_lds((const unsigned*)((const char*)(gbase) + (voff)[_i]), (PG8_LAS unsigned*)(lds + (bufoff) + ldsw + _i * 8192), 16, 0, 0); } while (0)
; #define PG8_LDA(dst, b, h) do { _Pragma("unroll") for (int m = 0; m < 4; ++m) _Pragma("unroll") for (int k = 0; k < 2; ++k) dst[m][k] = *(const PG8_LAS bf16x8*)(lds + PG8_SA(b, h) + aoff + m * 2048 + k * 1024); } while (0)
; #define PG8_LDB(dst, b, h) do { _Pragma("unroll") for (int n = 0; n < 2; ++n) _Pragma("unroll") for (int k = 0; k < 2; ++k) dst[n][k] = *(const PG8_LAS bf16x8*)(lds + PG8_SB(b, h) + boff + n * 2048 + k * 1024); } while (0)
; #define PG8_MMA(ai, bj, At, Bt) do { __builtin_amdgcn_s_setprio(1); _Pragma("unroll") for (int m = 0; m < 4; ++m) _Pragma("unroll") for (int n = 0; n < 2; ++n) _Pragma("unroll") for (int k = 0; k < 2; ++k) \
;         acc[ai][bj][m][n] = __builtin_amdgcn_mfma_f32_16x16x32_bf16(Bt[n][k], At[m][k], acc[ai][bj][m][n], 0, 0, 0); __builtin_amdgcn_s_setprio(0); } while (0)
; #define PG8_WAIT_V(n) asm volatile("s_waitcnt vmcnt(" #n ")" ::: "memory")
; #define PG8_WAIT_L(n) asm volatile("s_waitcnt lgkmcnt(" #n ")" ::: "memory")
; #define PG8_BAR __builtin_amdgcn_s_barrier()
; #define PG8_SCHED __builtin_amdgcn_sched_barrier(0)
; template <class Epi, class Sched>
; __device__ __forceinline__ void gemm_phase(PG8_LAS unsigned char* lds, const Gemm g, const Sched& S, const Epi& E, const int tid_in) {
;     ...
;             PG8_WAIT_V(6); PG8_BAR; PG8_MMA(1, 1, At, B1); PG8_BAR;
;             PG8_LDB(B0, 1, 0); PG8_SCHED; PG8_LDA(At, 1, 0); PG8_STAGE(PG8_SA(0, 1), a2 + hstepA, voffA);
;             PG8_WAIT_L(8); PG8_BAR; PG8_WAIT_L(0); PG8_MMA(0, 0, At, B0); PG8_BAR; PG8_SCHED;
;             PG8_LDB(B1, 1, 1); PG8_STAGE(PG8_SB(1, 0), b3, voffB);
;             PG8_BAR; PG8_WAIT_L(0); PG8_MMA(0, 1, At, B1); PG8_BAR;
;             PG8_LDA(At, 1, 1); PG8_STAGE(PG8_SA(1, 0), a3, voffA);
;             PG8_BAR; PG8_WAIT_L(0); PG8_MMA(1, 0, At, B0); PG8_BAR; PG8_SCHED;
;             PG8_STAGE(PG8_SB(1, 1), b3 + hstepB, voffB);
;             PG8_WAIT_V(6); PG8_BAR; PG8_MMA(1, 1, At, B1); PG8_BAR;
	s_add_u32 s28, s30, 0x40000
	s_addc_u32 s29, s31, 0
	s_mov_b32 m0, s59
	v_lshl_add_u64 v[132:133], s[28:29], 0, v[30:31]
	global_load_lds_dwordx4 v[132:133], off
	v_lshl_add_u64 v[132:133], s[28:29], 0, v[146:147]
	s_mov_b32 m0, s60
	s_nop 0
	global_load_lds_dwordx4 v[132:133], off
	s_waitcnt vmcnt(6)
	s_barrier
	s_setprio 1
	v_mfma_f32_16x16x32_bf16 v[56:59], v[226:229], v[194:197], v[56:59]
	v_mfma_f32_16x16x32_bf16 v[52:55], v[234:237], v[194:197], v[52:55]
	v_mfma_f32_16x16x32_bf16 v[40:43], v[226:229], v[202:205], v[40:43]
	v_mfma_f32_16x16x32_bf16 v[36:39], v[234:237], v[202:205], v[36:39]
	v_mfma_f32_16x16x32_bf16 v[20:23], v[226:229], v[210:213], v[20:23]
	v_mfma_f32_16x16x32_bf16 v[16:19], v[234:237], v[210:213], v[16:19]
	v_mfma_f32_16x16x32_bf16 v[4:7], v[226:229], v[218:221], v[4:7]
	v_mfma_f32_16x16x32_bf16 v[0:3], v[234:237], v[218:221], v[0:3]
	v_mfma_f32_16x16x32_bf16 v[56:59], v[230:233], v[198:201], v[56:59]
	v_mfma_f32_16x16x32_bf16 v[52:55], v[238:241], v[198:201], v[52:55]
	v_mfma_f32_16x16x32_bf16 v[40:43], v[230:233], v[206:209], v[40:43]
	v_mfma_f32_16x16x32_bf16 v[36:39], v[238:241], v[206:209], v[36:39]
	v_mfma_f32_16x16x32_bf16 v[20:23], v[230:233], v[214:217], v[20:23]
	v_mfma_f32_16x16x32_bf16 v[16:19], v[238:241], v[214:217], v[16:19]
	v_mfma_f32_16x16x32_bf16 v[4:7], v[230:233], v[222:225], v[4:7]
	v_mfma_f32_16x16x32_bf16 v[0:3], v[238:241], v[222:225], v[0:3]
	s_setprio 0
	v_add_u32_e32 v190, s46, v187
	s_barrier
	ds_read_b128 v[132:135], v190
	ds_read_b128 v[152:155], v190 offset:1024
	ds_read_b128 v[156:159], v190 offset:2048
	ds_read_b128 v[190:193], v190 offset:3072
	s_add_u32 s28, s34, 0x210000
	s_addc_u32 s29, s35, 0
	s_mov_b32 m0, s61
	v_lshl_add_u64 v[226:227], s[28:29], 0, v[28:29]
	ds_read_b128 v[194:197], v189 offset:32768
	ds_read_b128 v[198:201], v189 offset:33792
	ds_read_b128 v[202:205], v189 offset:34816
	ds_read_b128 v[206:209], v189 offset:35840
	ds_read_b128 v[210:213], v189 offset:36864
	ds_read_b128 v[214:217], v189 offset:37888
	ds_read_b128 v[218:221], v189 offset:38912
	ds_read_b128 v[222:225], v189 offset:39936
	global_load_lds_dwordx4 v[226:227], off
	v_lshl_add_u64 v[226:227], s[28:29], 0, v[144:145]
	s_mov_b32 m0, s62
	s_nop 0
	global_load_lds_dwordx4 v[226:227], off
	s_waitcnt lgkmcnt(8)
	s_barrier
	s_waitcnt lgkmcnt(0)
	s_setprio 1
	s_waitcnt lgkmcnt(0)
	v_mfma_f32_16x16x32_bf16 v[128:131], v[132:135], v[194:197], v[128:131]
	v_mfma_f32_16x16x32_bf16 v[124:127], v[156:159], v[194:197], v[124:127]
	v_mfma_f32_16x16x32_bf16 v[112:115], v[132:135], v[202:205], v[112:115]
	v_mfma_f32_16x16x32_bf16 v[108:111], v[156:159], v[202:205], v[108:111]
	v_mfma_f32_16x16x32_bf16 v[96:99], v[132:135], v[210:213], v[96:99]
	v_mfma_f32_16x16x32_bf16 v[92:95], v[156:159], v[210:213], v[92:95]
	v_mfma_f32_16x16x32_bf16 v[80:83], v[132:135], v[218:221], v[80:83]
	v_mfma_f32_16x16x32_bf16 v[76:79], v[156:159], v[218:221], v[76:79]
	v_mfma_f32_16x16x32_bf16 v[128:131], v[152:155], v[198:201], v[128:131]
	v_mfma_f32_16x16x32_bf16 v[124:127], v[190:193], v[198:201], v[124:127]
	v_mfma_f32_16x16x32_bf16 v[112:115], v[152:155], v[206:209], v[112:115]
	v_mfma_f32_16x16x32_bf16 v[108:111], v[190:193], v[206:209], v[108:111]
	v_mfma_f32_16x16x32_bf16 v[96:99], v[152:155], v[214:217], v[96:99]
	v_mfma_f32_16x16x32_bf16 v[92:95], v[190:193], v[214:217], v[92:95]
	v_mfma_f32_16x16x32_bf16 v[80:83], v[152:155], v[222:225], v[80:83]
	v_mfma_f32_16x16x32_bf16 v[76:79], v[190:193], v[222:225], v[76:79]
	s_setprio 0
	s_barrier
	s_mov_b32 m0, s63
	v_add_u32_e32 v238, s47, v187
	v_lshl_add_u64 v[136:137], v[136:137], 0, s[94:95]
	ds_read_b128 v[226:229], v238
	ds_read_b128 v[230:233], v238 offset:1024
	ds_read_b128 v[234:237], v238 offset:2048
	ds_read_b128 v[238:241], v238 offset:3072
	global_load_lds_dwordx4 v[136:137], off
	v_lshl_add_u64 v[136:137], v[138:139], 0, s[94:95]
	s_mov_b32 m0, s64
	s_nop 0
	global_load_lds_dwordx4 v[136:137], off
	s_barrier
	s_waitcnt lgkmcnt(0)
	s_setprio 1
	s_waitcnt lgkmcnt(0)
	v_mfma_f32_16x16x32_bf16 v[120:123], v[226:229], v[194:197], v[120:123]
	v_mfma_f32_16x16x32_bf16 v[116:119], v[234:237], v[194:197], v[116:119]
	v_mfma_f32_16x16x32_bf16 v[104:107], v[226:229], v[202:205], v[104:107]
	v_mfma_f32_16x16x32_bf16 v[100:103], v[234:237], v[202:205], v[100:103]
	v_mfma_f32_16x16x32_bf16 v[88:91], v[226:229], v[210:213], v[88:91]
	v_mfma_f32_16x16x32_bf16 v[84:87], v[234:237], v[210:213], v[84:87]
	v_mfma_f32_16x16x32_bf16 v[72:75], v[226:229], v[218:221], v[72:75]
	v_mfma_f32_16x16x32_bf16 v[68:71], v[234:237], v[218:221], v[68:71]
	v_mfma_f32_16x16x32_bf16 v[120:123], v[230:233], v[198:201], v[120:123]
	v_mfma_f32_16x16x32_bf16 v[116:119], v[238:241], v[198:201], v[116:119]
	v_mfma_f32_16x16x32_bf16 v[104:107], v[230:233], v[206:209], v[104:107]
	v_mfma_f32_16x16x32_bf16 v[100:103], v[238:241], v[206:209], v[100:103]
	v_mfma_f32_16x16x32_bf16 v[88:91], v[230:233], v[214:217], v[88:91]
	v_mfma_f32_16x16x32_bf16 v[84:87], v[238:241], v[214:217], v[84:87]
	v_mfma_f32_16x16x32_bf16 v[72:75], v[230:233], v[222:225], v[72:75]
	v_mfma_f32_16x16x32_bf16 v[68:71], v[238:241], v[222:225], v[68:71]
	s_setprio 0
	s_mov_b32 m0, s65
	v_lshl_add_u64 v[136:137], v[160:161], 0, s[94:95]
	s_barrier
	ds_read_b128 v[194:197], v189 offset:49152
	ds_read_b128 v[198:201], v189 offset:50176
	ds_read_b128 v[202:205], v189 offset:51200
	ds_read_b128 v[206:209], v189 offset:52224
	ds_read_b128 v[210:213], v189 offset:53248
	ds_read_b128 v[214:217], v189 offset:54272
	ds_read_b128 v[218:221], v189 offset:55296
	ds_read_b128 v[222:225], v189 offset:56320
	global_load_lds_dwordx4 v[136:137], off
	v_lshl_add_u64 v[136:137], v[242:243], 0, s[94:95]
	s_mov_b32 m0, s66
	s_nop 0
	global_load_lds_dwordx4 v[136:137], off
	s_barrier
; #define PG8_STAGE(bufoff, gbase, voff) do { _Pragma("unroll") for (int _i = 0; _i < 2; ++_i) \
;         __builtin_amdgcn_global_load_lds((const unsigned*)((const char*)(gbase) + (voff)[_i]), (PG8_LAS unsigned*)(lds + (bufoff) + ldsw + _i * 8192), 16, 0, 0); } while (0)
; #define PG8_MMA(ai, bj, At, Bt) do { __builtin_amdgcn_s_setprio(1); _Pragma("unroll") for (int m = 0; m < 4; ++m) _Pragma("unroll") for (int n = 0; n < 2; ++n) _Pragma("unroll") for (int k = 0; k < 2; ++k) \
;         acc[ai][bj][m][n] = __builtin_amdgcn_mfma_f32_16x16x32_bf16(Bt[n][k], At[m][k], acc[ai][bj][m][n], 0, 0, 0); __builtin_amdgcn_s_setprio(0); } while (0)
; #define PG8_WAIT_V(n) asm volatile("s_waitcnt vmcnt(" #n ")" ::: "memory")
; #define PG8_WAIT_L(n) asm volatile("s_waitcnt lgkmcnt(" #n ")" ::: "memory")
; #define PG8_BAR __builtin_amdgcn_s_barrier()
; #define PG8_SCHED __builtin_amdgcn_sched_barrier(0)
; template <class Epi, class Sched>
; __device__ __forceinline__ void gemm_phase(PG8_LAS unsigned char* lds, const Gemm g, const Sched& S, const Epi& E, const int tid_in) {
;     ...
;             PG8_BAR; PG8_WAIT_L(0); PG8_MMA(1, 0, At, B0); PG8_BAR; PG8_SCHED;
;             PG8_STAGE(PG8_SB(1, 1), b3 + hstepB, voffB);
;             PG8_WAIT_V(6); PG8_BAR; PG8_MMA(1, 1, At, B1); PG8_BAR;
;     __device__ __forceinline__ void operator()(const f32x4 (&acc)[2][2][4][2], const pg8::Unit& u, int wr, int wc, int fr, int fq) const {
;         const int row0 = u.pm * 256 + wr * 64 + fr, col0 = u.pn * 256 + wc * 32 + 8 * fq;
; #pragma unroll
;         for (int ai = 0; ai < 2; ++ai)
; #pragma unroll
;             for (int m = 0; m < 4; ++m) {
;                 const size_t row = (size_t)(row0 + ai * 128 + m * 16);
; #pragma unroll
;                 for (int bj = 0; bj < 2; ++bj) {
;                     float gt[8], mv[8], o[8];
;                     unpack8(*(const u32x4*)(Z + row * ZW + goff + col0 + bj * 128), gt);
;                     if (!first) unpack8(*(const u32x4*)(Mb + row * D + col0 + bj * 128), mv);
; #pragma unroll
;                     for (int n = 0; n < 2; ++n)
; #pragma unroll
;                         for (int j = 0; j < 4; ++j) o[4 * n + j] = (first ? 0.f : mv[4 * n + j]) + sigmoidf_(gt[4 * n + j]) * acc[ai][bj][m][n][j];
;                     *(u32x4*)(Mb + row * D + col0 + bj * 128) = pack8(o);
	s_waitcnt lgkmcnt(0)
	s_setprio 1
	s_waitcnt lgkmcnt(0)
	v_mfma_f32_16x16x32_bf16 v[64:67], v[132:135], v[194:197], v[64:67]
	v_mfma_f32_16x16x32_bf16 v[60:63], v[156:159], v[194:197], v[60:63]
	v_mfma_f32_16x16x32_bf16 v[48:51], v[132:135], v[202:205], v[48:51]
	v_mfma_f32_16x16x32_bf16 v[44:47], v[156:159], v[202:205], v[44:47]
	v_mfma_f32_16x16x32_bf16 v[32:35], v[132:135], v[210:213], v[32:35]
	v_mfma_f32_16x16x32_bf16 v[24:27], v[156:159], v[210:213], v[24:27]
	v_mfma_f32_16x16x32_bf16 v[12:15], v[132:135], v[218:221], v[12:15]
	v_mfma_f32_16x16x32_bf16 v[8:11], v[156:159], v[218:221], v[8:11]
	v_mfma_f32_16x16x32_bf16 v[64:67], v[152:155], v[198:201], v[64:67]
	v_mfma_f32_16x16x32_bf16 v[60:63], v[190:193], v[198:201], v[60:63]
	v_mfma_f32_16x16x32_bf16 v[48:51], v[152:155], v[206:209], v[48:51]
	v_mfma_f32_16x16x32_bf16 v[44:47], v[190:193], v[206:209], v[44:47]
	v_mfma_f32_16x16x32_bf16 v[32:35], v[152:155], v[214:217], v[32:35]
	v_mfma_f32_16x16x32_bf16 v[24:27], v[190:193], v[214:217], v[24:27]
	v_mfma_f32_16x16x32_bf16 v[12:15], v[152:155], v[222:225], v[12:15]
	v_mfma_f32_16x16x32_bf16 v[8:11], v[190:193], v[222:225], v[8:11]
	s_setprio 0
	s_barrier
	s_add_u32 s28, s30, 0x40080
	s_addc_u32 s29, s31, 0
	s_mov_b32 m0, s67
	v_lshl_add_u64 v[132:133], s[28:29], 0, v[30:31]
	global_load_lds_dwordx4 v[132:133], off
	v_lshl_add_u64 v[132:133], s[28:29], 0, v[146:147]
	s_mov_b32 m0, s68
	s_nop 0
	global_load_lds_dwordx4 v[132:133], off
	s_waitcnt vmcnt(6)
	s_barrier
	s_setprio 1
	v_mfma_f32_16x16x32_bf16 v[56:59], v[226:229], v[194:197], v[56:59]
	v_mfma_f32_16x16x32_bf16 v[52:55], v[234:237], v[194:197], v[52:55]
	v_mfma_f32_16x16x32_bf16 v[40:43], v[226:229], v[202:205], v[40:43]
	v_mfma_f32_16x16x32_bf16 v[36:39], v[234:237], v[202:205], v[36:39]
	v_mfma_f32_16x16x32_bf16 v[20:23], v[226:229], v[210:213], v[20:23]
	v_mfma_f32_16x16x32_bf16 v[16:19], v[234:237], v[210:213], v[16:19]
	v_mfma_f32_16x16x32_bf16 v[4:7], v[226:229], v[218:221], v[4:7]
	v_mfma_f32_16x16x32_bf16 v[0:3], v[234:237], v[218:221], v[0:3]
	v_mfma_f32_16x16x32_bf16 v[56:59], v[230:233], v[198:201], v[56:59]
	v_mfma_f32_16x16x32_bf16 v[52:55], v[238:241], v[198:201], v[52:55]
	v_mfma_f32_16x16x32_bf16 v[40:43], v[230:233], v[206:209], v[40:43]
	v_mfma_f32_16x16x32_bf16 v[36:39], v[238:241], v[206:209], v[36:39]
	v_mfma_f32_16x16x32_bf16 v[20:23], v[230:233], v[214:217], v[20:23]
	v_mfma_f32_16x16x32_bf16 v[16:19], v[238:241], v[214:217], v[16:19]
	v_mfma_f32_16x16x32_bf16 v[4:7], v[230:233], v[222:225], v[4:7]
	v_mfma_f32_16x16x32_bf16 v[0:3], v[238:241], v[222:225], v[0:3]
	s_setprio 0
	s_add_i32 s74, s74, 2
	s_add_u32 s72, s72, 0x100
	s_addc_u32 s73, s73, 0
	s_cmp_gt_u32 s74, 13
	s_mov_b64 s[28:29], s[4:5]
	s_barrier
	s_cbranch_scc0 .LBB0_1749
	v_lshl_add_u32 v154, s0, 8, v186
	v_lshl_or_b32 v152, s26, 8, v188
	v_lshlrev_b32_e32 v234, 1, v152
	v_mad_u32_u24 v232, v154, s33, v234
	v_lshl_add_u32 v233, v154, 11, v234
	v_mov_b32_e32 v235, v232
	v_add_u32_e32 v236, 0x42000, v232
	global_load_dwordx4 v[200:203], v235, s[18:19] offset:2048
	global_load_dwordx4 v[204:207], v235, s[18:19] offset:2304
	global_load_dwordx4 v[208:211], v236, s[18:19] offset:2048
	global_load_dwordx4 v[212:215], v236, s[18:19] offset:2304
	s_andn2_b64 vcc, exec, s[16:17]
	s_cbranch_vccnz .Lem_skip0
	v_mov_b32_e32 v235, v233
	v_add_u32_e32 v236, 0x8000, v233
	global_load_dwordx4 v[216:219], v235, s[10:11]
	global_load_dwordx4 v[220:223], v235, s[10:11] offset:256
	global_load_dwordx4 v[224:227], v236, s[10:11]
	global_load_dwordx4 v[228:231], v236, s[10:11] offset:256
.Lem_skip0:
	s_waitcnt vmcnt(0)
	v_mov_b64_e32 v[132:133], s[18:19]
	v_ashrrev_i32_e32 v153, 31, v152
	v_mad_i64_i32 v[132:133], s[4:5], v154, s33, v[132:133]
	v_lshl_add_u64 v[160:161], v[152:153], 1, v[132:133]
	s_nop 1
	v_mov_b64_e32 v[132:133], v[200:201]
	v_mov_b64_e32 v[134:135], v[202:203]
	v_ashrrev_i32_e32 v155, 31, v154
	v_lshlrev_b64 v[136:137], 11, v[154:155]
	v_cndmask_b32_e64 v138, 0, 1, s[16:17]
	v_lshl_add_u64 v[136:137], s[10:11], 0, v[136:137]
	v_mov_b32_e32 v158, 0
	v_cmp_ne_u32_e64 s[4:5], 1, v138
	s_andn2_b64 vcc, exec, s[16:17]
	v_lshl_add_u64 v[156:157], v[152:153], 1, v[136:137]
	v_mov_b32_e32 v194, 0
	v_mov_b32_e32 v195, 0
	v_mov_b32_e32 v193, 0
	v_mov_b32_e32 v192, 0
	v_mov_b32_e32 v190, 0
	v_mov_b32_e32 v191, 0
	v_mov_b32_e32 v155, 0
	v_mov_b32_e32 v159, 0
	s_cbranch_vccnz .LBB0_1752
	s_nop 1
	v_mov_b64_e32 v[196:197], v[216:217]
	v_mov_b64_e32 v[198:199], v[218:219]
	v_lshlrev_b32_e32 v194, 16, v196
	v_and_b32_e32 v195, 0xffff0000, v196
	v_lshlrev_b32_e32 v193, 16, v197
	v_and_b32_e32 v192, 0xffff0000, v197
	v_lshlrev_b32_e32 v190, 16, v198
	v_and_b32_e32 v191, 0xffff0000, v198
	v_lshlrev_b32_e32 v155, 16, v199
	v_and_b32_e32 v159, 0xffff0000, v199
; __device__ __forceinline__ void unpack8(const u32x4 w, float (&f)[8]) { f[0] = bflo(w.x); f[1] = bfhi(w.x); f[2] = bflo(w.y); f[3] = bfhi(w.y); f[4] = bflo(w.z); f[5] = bfhi(w.z); f[6] = bflo(w.w); f[7] = bfhi(w.w); }
; __device__ __forceinline__ u32x4 pack8(const float (&f)[8]) { u32x4 w; w.x = pk2(f[0], f[1]); w.y = pk2(f[2], f[3]); w.z = pk2(f[4], f[5]); w.w = pk2(f[6], f[7]); return w; }
; __device__ __forceinline__ float sigmoidf_(float x) { return __builtin_amdgcn_rcpf(1.0f + __expf(-x)); }
;     __device__ __forceinline__ void operator()(const f32x4 (&acc)[2][2][4][2], const pg8::Unit& u, int wr, int wc, int fr, int fq) const {
;     ...
;                 const size_t row = (size_t)(row0 + ai * 128 + m * 16);
; #pragma unroll
;                 for (int bj = 0; bj < 2; ++bj) {
;                     float gt[8], mv[8], o[8];
;                     unpack8(*(const u32x4*)(Z + row * ZW + goff + col0 + bj * 128), gt);
;                     if (!first) unpack8(*(const u32x4*)(Mb + row * D + col0 + bj * 128), mv);
; #pragma unroll
;                     for (int n = 0; n < 2; ++n)
; #pragma unroll
;                         for (int j = 0; j < 4; ++j) o[4 * n + j] = (first ? 0.f : mv[4 * n + j]) + sigmoidf_(gt[4 * n + j]) * acc[ai][bj][m][n][j];
;                     *(u32x4*)(Mb + row * D + col0 + bj * 128) = pack8(o);
.LBB0_1752:
	v_lshlrev_b32_e32 v136, 16, v132
	v_and_b32_e32 v132, 0xffff0000, v132
	v_mul_f32_e32 v136, 0xbfb8aa3b, v136
	v_exp_f32_e32 v136, v136
	v_mul_f32_e32 v132, 0xbfb8aa3b, v132
	v_exp_f32_e32 v132, v132
	v_cndmask_b32_e64 v194, 0, v194, s[16:17]
	v_add_f32_e32 v136, 1.0, v136
	v_rcp_f32_e32 v136, v136
	v_add_f32_e32 v132, 1.0, v132
	v_rcp_f32_e32 v132, v132
	v_lshlrev_b32_e32 v137, 16, v133
	v_fmac_f32_e32 v194, v128, v136
	v_cndmask_b32_e64 v128, 0, v195, s[16:17]
	v_and_b32_e32 v133, 0xffff0000, v133
	v_fmac_f32_e32 v128, v129, v132
	v_mul_f32_e32 v129, 0xbfb8aa3b, v137
	v_exp_f32_e32 v129, v129
	v_mul_f32_e32 v132, 0xbfb8aa3b, v133
	v_exp_f32_e32 v132, v132
	v_lshlrev_b32_e32 v138, 16, v134
	v_add_f32_e32 v129, 1.0, v129
	v_rcp_f32_e32 v129, v129
	v_add_f32_e32 v132, 1.0, v132
	v_mul_f32_e32 v136, 0xbfb8aa3b, v138
	v_rcp_f32_e32 v132, v132
	v_exp_f32_e32 v136, v136
	v_cndmask_b32_e64 v133, 0, v193, s[16:17]
	v_and_b32_e32 v134, 0xffff0000, v134
	v_fmac_f32_e32 v133, v130, v129
	v_cndmask_b32_e64 v129, 0, v192, s[16:17]
	v_fmac_f32_e32 v129, v131, v132
	v_add_f32_e32 v130, 1.0, v136
	v_mul_f32_e32 v131, 0xbfb8aa3b, v134
	v_rcp_f32_e32 v130, v130
	v_exp_f32_e32 v131, v131
	v_lshlrev_b32_e32 v139, 16, v135
	v_and_b32_e32 v135, 0xffff0000, v135
	v_cndmask_b32_e64 v132, 0, v190, s[16:17]
	v_fmac_f32_e32 v132, v124, v130
	v_add_f32_e32 v124, 1.0, v131
	v_mul_f32_e32 v131, 0xbfb8aa3b, v139
	v_mul_f32_e32 v134, 0xbfb8aa3b, v135
	v_rcp_f32_e32 v124, v124
	v_exp_f32_e32 v131, v131
	v_exp_f32_e32 v134, v134
	v_cndmask_b32_e64 v130, 0, v191, s[16:17]
	v_fmac_f32_e32 v130, v125, v124
	v_add_f32_e32 v124, 1.0, v131
	v_add_f32_e32 v125, 1.0, v134
	v_rcp_f32_e32 v124, v124
	v_rcp_f32_e32 v125, v125
	v_cndmask_b32_e64 v131, 0, v155, s[16:17]
	v_cndmask_b32_e64 v134, 0, v159, s[16:17]
	v_fmac_f32_e32 v131, v126, v124
	v_fmac_f32_e32 v134, v127, v125
	v_cvt_pk_bf16_f32 v124, v194, v128
	v_cvt_pk_bf16_f32 v125, v133, v129
	v_cvt_pk_bf16_f32 v126, v132, v130
	v_cvt_pk_bf16_f32 v127, v131, v134
	global_store_dwordx4 v[156:157], v[124:127], off
	s_nop 1
	v_mov_b64_e32 v[124:125], v[204:205]
	v_mov_b64_e32 v[126:127], v[206:207]
	s_and_b64 vcc, exec, s[4:5]
	v_mov_b32_e32 v159, 0
	v_mov_b32_e32 v128, 0
	v_mov_b32_e32 v129, 0
	v_mov_b32_e32 v130, 0
	v_mov_b32_e32 v131, 0
	v_mov_b32_e32 v132, 0
	v_mov_b32_e32 v133, 0
	s_cbranch_vccnz .LBB0_1754
	s_nop 1
	v_mov_b64_e32 v[134:135], v[220:221]
	v_mov_b64_e32 v[136:137], v[222:223]
	v_lshlrev_b32_e32 v132, 16, v134
	v_and_b32_e32 v133, 0xffff0000, v134
	v_lshlrev_b32_e32 v130, 16, v135
	v_and_b32_e32 v131, 0xffff0000, v135
	v_lshlrev_b32_e32 v128, 16, v136
	v_and_b32_e32 v129, 0xffff0000, v136
	v_lshlrev_b32_e32 v158, 16, v137
	v_and_b32_e32 v159, 0xffff0000, v137
.LBB0_1754:
	v_lshlrev_b32_e32 v134, 16, v124
	v_and_b32_e32 v135, 0xffff0000, v124
	v_lshlrev_b32_e32 v136, 16, v125
	v_and_b32_e32 v137, 0xffff0000, v125
	v_mul_f32_e32 v124, 0xbfb8aa3b, v134
	v_mul_f32_e32 v125, 0xbfb8aa3b, v135
	v_exp_f32_e32 v124, v124
	v_exp_f32_e32 v125, v125
	v_lshlrev_b32_e32 v138, 16, v126
	v_and_b32_e32 v126, 0xffff0000, v126
	v_add_f32_e32 v124, 1.0, v124
	v_add_f32_e32 v125, 1.0, v125
	v_rcp_f32_e32 v124, v124
	v_rcp_f32_e32 v125, v125
	v_lshlrev_b32_e32 v139, 16, v127
	v_and_b32_e32 v127, 0xffff0000, v127
	s_and_b64 vcc, exec, s[4:5]
	v_pk_fma_f32 v[120:121], v[120:121], v[124:125], v[132:133]
	v_mul_f32_e32 v124, 0xbfb8aa3b, v136
	v_mul_f32_e32 v125, 0xbfb8aa3b, v137
	v_exp_f32_e32 v124, v124
	v_exp_f32_e32 v125, v125
	v_mov_b32_e32 v132, 0
	v_mov_b32_e32 v133, 0
	v_add_f32_e32 v124, 1.0, v124
	v_add_f32_e32 v125, 1.0, v125
	v_rcp_f32_e32 v124, v124
	v_rcp_f32_e32 v125, v125
	s_nop 0
	v_pk_fma_f32 v[122:123], v[122:123], v[124:125], v[130:131]
	v_mul_f32_e32 v124, 0xbfb8aa3b, v138
	v_mul_f32_e32 v125, 0xbfb8aa3b, v126
	v_exp_f32_e32 v124, v124
	v_exp_f32_e32 v125, v125
	v_mov_b32_e32 v130, 0
	v_mov_b32_e32 v131, 0
	v_add_f32_e32 v124, 1.0, v124
	v_add_f32_e32 v125, 1.0, v125
	v_rcp_f32_e32 v124, v124
	v_rcp_f32_e32 v125, v125
	s_nop 0
	v_pk_fma_f32 v[124:125], v[116:117], v[124:125], v[128:129]
	v_mul_f32_e32 v116, 0xbfb8aa3b, v139
	v_mul_f32_e32 v117, 0xbfb8aa3b, v127
	v_exp_f32_e32 v116, v116
	v_exp_f32_e32 v117, v117
	v_mov_b32_e32 v128, 0
	v_mov_b32_e32 v129, 0
	v_add_f32_e32 v116, 1.0, v116
	v_add_f32_e32 v117, 1.0, v117
	v_rcp_f32_e32 v116, v116
	v_rcp_f32_e32 v117, v117
	s_nop 0
	v_pk_fma_f32 v[126:127], v[118:119], v[116:117], v[158:159]
	v_cvt_pk_bf16_f32 v116, v120, v121
	v_cvt_pk_bf16_f32 v117, v122, v123
	v_cvt_pk_bf16_f32 v118, v124, v125
	v_cvt_pk_bf16_f32 v119, v126, v127
	global_store_dwordx4 v[156:157], v[116:119], off offset:256
	v_mov_b32_e32 v122, 0
	v_mov_b32_e32 v126, 0
	v_or_b32_e32 v116, 16, v154
	v_ashrrev_i32_e32 v117, 31, v116
	v_mov_b64_e32 v[118:119], s[18:19]
	v_lshlrev_b64 v[120:121], 11, v[116:117]
	v_mad_i64_i32 v[116:117], s[28:29], v116, s33, v[118:119]
	v_lshl_add_u64 v[124:125], v[152:153], 1, v[116:117]
	s_nop 1
	v_mov_b64_e32 v[116:117], v[208:209]
	v_mov_b64_e32 v[118:119], v[210:211]
	v_lshl_add_u64 v[120:121], s[10:11], 0, v[120:121]
	v_lshl_add_u64 v[120:121], v[152:153], 1, v[120:121]
	v_mov_b32_e32 v127, 0
	s_cbranch_vccnz .LBB0_1756
	s_nop 1
	v_mov_b64_e32 v[134:135], v[224:225]
	v_mov_b64_e32 v[136:137], v[226:227]
	v_lshlrev_b32_e32 v132, 16, v134
	v_and_b32_e32 v133, 0xffff0000, v134
	v_lshlrev_b32_e32 v130, 16, v135
	v_and_b32_e32 v131, 0xffff0000, v135
	v_lshlrev_b32_e32 v128, 16, v136
	v_and_b32_e32 v129, 0xffff0000, v136
	v_lshlrev_b32_e32 v126, 16, v137
	v_and_b32_e32 v127, 0xffff0000, v137
; __device__ __forceinline__ void unpack8(const u32x4 w, float (&f)[8]) { f[0] = bflo(w.x); f[1] = bfhi(w.x); f[2] = bflo(w.y); f[3] = bfhi(w.y); f[4] = bflo(w.z); f[5] = bfhi(w.z); f[6] = bflo(w.w); f[7] = bfhi(w.w); }
; __device__ __forceinline__ u32x4 pack8(const float (&f)[8]) { u32x4 w; w.x = pk2(f[0], f[1]); w.y = pk2(f[2], f[3]); w.z = pk2(f[4], f[5]); w.w = pk2(f[6], f[7]); return w; }
; __device__ __forceinline__ float sigmoidf_(float x) { return __builtin_amdgcn_rcpf(1.0f + __expf(-x)); }
;     __device__ __forceinline__ void operator()(const f32x4 (&acc)[2][2][4][2], const pg8::Unit& u, int wr, int wc, int fr, int fq) const {
;     ...
;                 const size_t row = (size_t)(row0 + ai * 128 + m * 16);
; #pragma unroll
;                 for (int bj = 0; bj < 2; ++bj) {
;                     float gt[8], mv[8], o[8];
;                     unpack8(*(const u32x4*)(Z + row * ZW + goff + col0 + bj * 128), gt);
;                     if (!first) unpack8(*(const u32x4*)(Mb + row * D + col0 + bj * 128), mv);
; #pragma unroll
;                     for (int n = 0; n < 2; ++n)
; #pragma unroll
;                         for (int j = 0; j < 4; ++j) o[4 * n + j] = (first ? 0.f : mv[4 * n + j]) + sigmoidf_(gt[4 * n + j]) * acc[ai][bj][m][n][j];
;                     *(u32x4*)(Mb + row * D + col0 + bj * 128) = pack8(o);
.LBB0_1756:
	v_lshlrev_b32_e32 v123, 16, v116
	v_and_b32_e32 v134, 0xffff0000, v116
	v_lshlrev_b32_e32 v135, 16, v117
	v_and_b32_e32 v136, 0xffff0000, v117
	v_mul_f32_e32 v116, 0xbfb8aa3b, v123
	v_mul_f32_e32 v117, 0xbfb8aa3b, v134
	v_exp_f32_e32 v116, v116
	v_exp_f32_e32 v117, v117
	v_lshlrev_b32_e32 v137, 16, v118
	v_and_b32_e32 v118, 0xffff0000, v118
	v_add_f32_e32 v116, 1.0, v116
	v_add_f32_e32 v117, 1.0, v117
	v_rcp_f32_e32 v116, v116
	v_rcp_f32_e32 v117, v117
	v_lshlrev_b32_e32 v138, 16, v119
	v_and_b32_e32 v119, 0xffff0000, v119
	s_and_b64 vcc, exec, s[4:5]
	v_pk_fma_f32 v[112:113], v[112:113], v[116:117], v[132:133]
	v_mul_f32_e32 v116, 0xbfb8aa3b, v135
	v_mul_f32_e32 v117, 0xbfb8aa3b, v136
	v_exp_f32_e32 v116, v116
	v_exp_f32_e32 v117, v117
	v_mov_b32_e32 v123, 0
	v_add_f32_e32 v116, 1.0, v116
	v_add_f32_e32 v117, 1.0, v117
	v_rcp_f32_e32 v116, v116
	v_rcp_f32_e32 v117, v117
	s_nop 0
	v_pk_fma_f32 v[114:115], v[114:115], v[116:117], v[130:131]
	v_mul_f32_e32 v116, 0xbfb8aa3b, v137
	v_mul_f32_e32 v117, 0xbfb8aa3b, v118
	v_exp_f32_e32 v116, v116
	v_exp_f32_e32 v117, v117
	v_add_f32_e32 v116, 1.0, v116
	v_add_f32_e32 v117, 1.0, v117
	v_rcp_f32_e32 v116, v116
	v_rcp_f32_e32 v117, v117
	s_nop 0
	v_pk_fma_f32 v[116:117], v[108:109], v[116:117], v[128:129]
	v_mul_f32_e32 v108, 0xbfb8aa3b, v138
	v_mul_f32_e32 v109, 0xbfb8aa3b, v119
	v_exp_f32_e32 v108, v108
	v_exp_f32_e32 v109, v109
	v_add_f32_e32 v108, 1.0, v108
	v_add_f32_e32 v109, 1.0, v109
	v_rcp_f32_e32 v108, v108
	v_rcp_f32_e32 v109, v109
	s_nop 0
	v_pk_fma_f32 v[118:119], v[110:111], v[108:109], v[126:127]
	v_cvt_pk_bf16_f32 v108, v112, v113
	v_cvt_pk_bf16_f32 v109, v114, v115
	v_cvt_pk_bf16_f32 v110, v116, v117
	v_cvt_pk_bf16_f32 v111, v118, v119
	global_store_dwordx4 v[120:121], v[108:111], off
	s_nop 1
	v_mov_b64_e32 v[108:109], v[212:213]
	v_mov_b64_e32 v[110:111], v[214:215]
	v_mov_b32_e32 v112, 0
	v_mov_b32_e32 v113, 0
	v_mov_b32_e32 v114, 0
	v_mov_b32_e32 v115, 0
	v_mov_b32_e32 v116, 0
	v_mov_b32_e32 v117, 0
	s_cbranch_vccnz .LBB0_1758
	s_nop 1
	v_mov_b64_e32 v[122:123], v[228:229]
	v_mov_b64_e32 v[124:125], v[230:231]
	v_lshlrev_b32_e32 v116, 16, v122
	v_and_b32_e32 v117, 0xffff0000, v122
	v_lshlrev_b32_e32 v114, 16, v123
	v_and_b32_e32 v115, 0xffff0000, v123
	v_lshlrev_b32_e32 v112, 16, v124
	v_and_b32_e32 v113, 0xffff0000, v124
	v_lshlrev_b32_e32 v122, 16, v125
	v_and_b32_e32 v123, 0xffff0000, v125
.LBB0_1758:
	v_lshlrev_b32_e32 v118, 16, v108
	v_and_b32_e32 v119, 0xffff0000, v108
	v_lshlrev_b32_e32 v124, 16, v109
	v_and_b32_e32 v125, 0xffff0000, v109
	v_mul_f32_e32 v108, 0xbfb8aa3b, v118
	v_mul_f32_e32 v109, 0xbfb8aa3b, v119
	v_exp_f32_e32 v108, v108
	v_exp_f32_e32 v109, v109
	v_lshlrev_b32_e32 v126, 16, v110
	v_and_b32_e32 v110, 0xffff0000, v110
	v_add_f32_e32 v108, 1.0, v108
	v_add_f32_e32 v109, 1.0, v109
	v_rcp_f32_e32 v108, v108
	v_rcp_f32_e32 v109, v109
	v_lshlrev_b32_e32 v127, 16, v111
	v_and_b32_e32 v111, 0xffff0000, v111
	s_and_b64 vcc, exec, s[4:5]
	v_pk_fma_f32 v[104:105], v[104:105], v[108:109], v[116:117]
	v_mul_f32_e32 v108, 0xbfb8aa3b, v124
	v_mul_f32_e32 v109, 0xbfb8aa3b, v125
	v_exp_f32_e32 v108, v108
	v_exp_f32_e32 v109, v109
	v_mov_b32_e32 v116, 0
	v_mov_b32_e32 v117, 0
	v_add_f32_e32 v108, 1.0, v108
	v_add_f32_e32 v109, 1.0, v109
	v_rcp_f32_e32 v108, v108
	v_rcp_f32_e32 v109, v109
	s_nop 0
	v_pk_fma_f32 v[106:107], v[106:107], v[108:109], v[114:115]
	v_mul_f32_e32 v108, 0xbfb8aa3b, v126
	v_mul_f32_e32 v109, 0xbfb8aa3b, v110
	v_exp_f32_e32 v108, v108
	v_exp_f32_e32 v109, v109
	v_mov_b32_e32 v114, 0
	v_mov_b32_e32 v115, 0
	v_add_f32_e32 v108, 1.0, v108
	v_add_f32_e32 v109, 1.0, v109
	v_rcp_f32_e32 v108, v108
	v_rcp_f32_e32 v109, v109
	s_nop 0
	v_pk_fma_f32 v[108:109], v[100:101], v[108:109], v[112:113]
	v_mul_f32_e32 v100, 0xbfb8aa3b, v127
	v_mul_f32_e32 v101, 0xbfb8aa3b, v111
	v_exp_f32_e32 v100, v100
	v_exp_f32_e32 v101, v101
	v_mov_b32_e32 v112, 0
	v_mov_b32_e32 v113, 0
	v_add_f32_e32 v100, 1.0, v100
	v_add_f32_e32 v101, 1.0, v101
	v_rcp_f32_e32 v100, v100
	v_rcp_f32_e32 v101, v101
	s_nop 0
	v_pk_fma_f32 v[110:111], v[102:103], v[100:101], v[122:123]
	v_cvt_pk_bf16_f32 v100, v104, v105
	v_cvt_pk_bf16_f32 v101, v106, v107
	v_cvt_pk_bf16_f32 v102, v108, v109
	v_cvt_pk_bf16_f32 v103, v110, v111
	global_store_dwordx4 v[120:121], v[100:103], off offset:256
	v_mov_b32_e32 v106, 0
	v_mov_b32_e32 v110, 0
	v_add_u32_e32 v235, 0x84000, v232
	v_add_u32_e32 v236, 0xc6000, v232
	global_load_dwordx4 v[200:203], v235, s[18:19] offset:2048
	global_load_dwordx4 v[204:207], v235, s[18:19] offset:2304
	global_load_dwordx4 v[208:211], v236, s[18:19] offset:2048
	global_load_dwordx4 v[212:215], v236, s[18:19] offset:2304
	s_and_b64 vcc, exec, s[4:5]
	s_cbranch_vccnz .Lem_skip1
	v_add_u32_e32 v235, 0x10000, v233
	v_add_u32_e32 v236, 0x18000, v233
	global_load_dwordx4 v[216:219], v235, s[10:11]
	global_load_dwordx4 v[220:223], v235, s[10:11] offset:256
	global_load_dwordx4 v[224:227], v236, s[10:11]
	global_load_dwordx4 v[228:231], v236, s[10:11] offset:256
.Lem_skip1:
	s_waitcnt vmcnt(0)
	v_or_b32_e32 v100, 32, v154
	v_ashrrev_i32_e32 v101, 31, v100
	v_mov_b64_e32 v[102:103], s[18:19]
	v_lshlrev_b64 v[104:105], 11, v[100:101]
	v_mad_i64_i32 v[100:101], s[28:29], v100, s33, v[102:103]
	v_lshl_add_u64 v[108:109], v[152:153], 1, v[100:101]
	s_nop 1
	v_mov_b64_e32 v[100:101], v[200:201]
	v_mov_b64_e32 v[102:103], v[202:203]
	v_lshl_add_u64 v[104:105], s[10:11], 0, v[104:105]
	v_lshl_add_u64 v[104:105], v[152:153], 1, v[104:105]
	v_mov_b32_e32 v111, 0
	s_cbranch_vccnz .LBB0_1760
	s_nop 1
	v_mov_b64_e32 v[118:119], v[216:217]
	v_mov_b64_e32 v[120:121], v[218:219]
	v_lshlrev_b32_e32 v116, 16, v118
	v_and_b32_e32 v117, 0xffff0000, v118
	v_lshlrev_b32_e32 v114, 16, v119
	v_and_b32_e32 v115, 0xffff0000, v119
	v_lshlrev_b32_e32 v112, 16, v120
	v_and_b32_e32 v113, 0xffff0000, v120
	v_lshlrev_b32_e32 v110, 16, v121
	v_and_b32_e32 v111, 0xffff0000, v121
; __device__ __forceinline__ void unpack8(const u32x4 w, float (&f)[8]) { f[0] = bflo(w.x); f[1] = bfhi(w.x); f[2] = bflo(w.y); f[3] = bfhi(w.y); f[4] = bflo(w.z); f[5] = bfhi(w.z); f[6] = bflo(w.w); f[7] = bfhi(w.w); }
; __device__ __forceinline__ u32x4 pack8(const float (&f)[8]) { u32x4 w; w.x = pk2(f[0], f[1]); w.y = pk2(f[2], f[3]); w.z = pk2(f[4], f[5]); w.w = pk2(f[6], f[7]); return w; }
; __device__ __forceinline__ float sigmoidf_(float x) { return __builtin_amdgcn_rcpf(1.0f + __expf(-x)); }
;     __device__ __forceinline__ void operator()(const f32x4 (&acc)[2][2][4][2], const pg8::Unit& u, int wr, int wc, int fr, int fq) const {
;     ...
;                 const size_t row = (size_t)(row0 + ai * 128 + m * 16);
; #pragma unroll
;                 for (int bj = 0; bj < 2; ++bj) {
;                     float gt[8], mv[8], o[8];
;                     unpack8(*(const u32x4*)(Z + row * ZW + goff + col0 + bj * 128), gt);
;                     if (!first) unpack8(*(const u32x4*)(Mb + row * D + col0 + bj * 128), mv);
; #pragma unroll
;                     for (int n = 0; n < 2; ++n)
; #pragma unroll
;                         for (int j = 0; j < 4; ++j) o[4 * n + j] = (first ? 0.f : mv[4 * n + j]) + sigmoidf_(gt[4 * n + j]) * acc[ai][bj][m][n][j];
;                     *(u32x4*)(Mb + row * D + col0 + bj * 128) = pack8(o);
.LBB0_1760:
	v_lshlrev_b32_e32 v107, 16, v100
	v_and_b32_e32 v118, 0xffff0000, v100
	v_lshlrev_b32_e32 v119, 16, v101
	v_and_b32_e32 v120, 0xffff0000, v101
	v_mul_f32_e32 v100, 0xbfb8aa3b, v107
	v_mul_f32_e32 v101, 0xbfb8aa3b, v118
	v_exp_f32_e32 v100, v100
	v_exp_f32_e32 v101, v101
	v_lshlrev_b32_e32 v121, 16, v102
	v_and_b32_e32 v102, 0xffff0000, v102
	v_add_f32_e32 v100, 1.0, v100
	v_add_f32_e32 v101, 1.0, v101
	v_rcp_f32_e32 v100, v100
	v_rcp_f32_e32 v101, v101
	v_lshlrev_b32_e32 v122, 16, v103
	v_and_b32_e32 v103, 0xffff0000, v103
	s_and_b64 vcc, exec, s[4:5]
	v_pk_fma_f32 v[96:97], v[96:97], v[100:101], v[116:117]
	v_mul_f32_e32 v100, 0xbfb8aa3b, v119
	v_mul_f32_e32 v101, 0xbfb8aa3b, v120
	v_exp_f32_e32 v100, v100
	v_exp_f32_e32 v101, v101
	v_mov_b32_e32 v107, 0
	v_add_f32_e32 v100, 1.0, v100
	v_add_f32_e32 v101, 1.0, v101
	v_rcp_f32_e32 v100, v100
	v_rcp_f32_e32 v101, v101
	s_nop 0
	v_pk_fma_f32 v[98:99], v[98:99], v[100:101], v[114:115]
	v_mul_f32_e32 v100, 0xbfb8aa3b, v121
	v_mul_f32_e32 v101, 0xbfb8aa3b, v102
	v_exp_f32_e32 v100, v100
	v_exp_f32_e32 v101, v101
	v_add_f32_e32 v100, 1.0, v100
	v_add_f32_e32 v101, 1.0, v101
	v_rcp_f32_e32 v100, v100
	v_rcp_f32_e32 v101, v101
	s_nop 0
	v_pk_fma_f32 v[100:101], v[92:93], v[100:101], v[112:113]
	v_mul_f32_e32 v92, 0xbfb8aa3b, v122
	v_mul_f32_e32 v93, 0xbfb8aa3b, v103
	v_exp_f32_e32 v92, v92
	v_exp_f32_e32 v93, v93
	v_add_f32_e32 v92, 1.0, v92
	v_add_f32_e32 v93, 1.0, v93
	v_rcp_f32_e32 v92, v92
	v_rcp_f32_e32 v93, v93
	s_nop 0
	v_pk_fma_f32 v[102:103], v[94:95], v[92:93], v[110:111]
	v_cvt_pk_bf16_f32 v92, v96, v97
	v_cvt_pk_bf16_f32 v93, v98, v99
	v_cvt_pk_bf16_f32 v94, v100, v101
	v_cvt_pk_bf16_f32 v95, v102, v103
	global_store_dwordx4 v[104:105], v[92:95], off
	s_nop 1
	v_mov_b64_e32 v[92:93], v[204:205]
	v_mov_b64_e32 v[94:95], v[206:207]
	v_mov_b32_e32 v96, 0
	v_mov_b32_e32 v97, 0
	v_mov_b32_e32 v98, 0
	v_mov_b32_e32 v99, 0
	v_mov_b32_e32 v100, 0
	v_mov_b32_e32 v101, 0
	s_cbranch_vccnz .LBB0_1762
	s_nop 1
	v_mov_b64_e32 v[106:107], v[220:221]
	v_mov_b64_e32 v[108:109], v[222:223]
	v_lshlrev_b32_e32 v100, 16, v106
	v_and_b32_e32 v101, 0xffff0000, v106
	v_lshlrev_b32_e32 v98, 16, v107
	v_and_b32_e32 v99, 0xffff0000, v107
	v_lshlrev_b32_e32 v96, 16, v108
	v_and_b32_e32 v97, 0xffff0000, v108
	v_lshlrev_b32_e32 v106, 16, v109
	v_and_b32_e32 v107, 0xffff0000, v109
.LBB0_1762:
	v_lshlrev_b32_e32 v102, 16, v92
	v_and_b32_e32 v103, 0xffff0000, v92
	v_lshlrev_b32_e32 v108, 16, v93
	v_and_b32_e32 v109, 0xffff0000, v93
	v_mul_f32_e32 v92, 0xbfb8aa3b, v102
	v_mul_f32_e32 v93, 0xbfb8aa3b, v103
	v_exp_f32_e32 v92, v92
	v_exp_f32_e32 v93, v93
	v_lshlrev_b32_e32 v110, 16, v94
	v_and_b32_e32 v94, 0xffff0000, v94
	v_add_f32_e32 v92, 1.0, v92
	v_add_f32_e32 v93, 1.0, v93
	v_rcp_f32_e32 v92, v92
	v_rcp_f32_e32 v93, v93
	v_lshlrev_b32_e32 v111, 16, v95
	v_and_b32_e32 v95, 0xffff0000, v95
	s_and_b64 vcc, exec, s[4:5]
	v_pk_fma_f32 v[88:89], v[88:89], v[92:93], v[100:101]
	v_mul_f32_e32 v92, 0xbfb8aa3b, v108
	v_mul_f32_e32 v93, 0xbfb8aa3b, v109
	v_exp_f32_e32 v92, v92
	v_exp_f32_e32 v93, v93
	v_mov_b32_e32 v100, 0
	v_mov_b32_e32 v101, 0
	v_add_f32_e32 v92, 1.0, v92
	v_add_f32_e32 v93, 1.0, v93
	v_rcp_f32_e32 v92, v92
	v_rcp_f32_e32 v93, v93
	s_nop 0
	v_pk_fma_f32 v[90:91], v[90:91], v[92:93], v[98:99]
	v_mul_f32_e32 v92, 0xbfb8aa3b, v110
	v_mul_f32_e32 v93, 0xbfb8aa3b, v94
	v_exp_f32_e32 v92, v92
	v_exp_f32_e32 v93, v93
	v_mov_b32_e32 v98, 0
	v_mov_b32_e32 v99, 0
	v_add_f32_e32 v92, 1.0, v92
	v_add_f32_e32 v93, 1.0, v93
	v_rcp_f32_e32 v92, v92
	v_rcp_f32_e32 v93, v93
	s_nop 0
	v_pk_fma_f32 v[92:93], v[84:85], v[92:93], v[96:97]
	v_mul_f32_e32 v84, 0xbfb8aa3b, v111
	v_mul_f32_e32 v85, 0xbfb8aa3b, v95
	v_exp_f32_e32 v84, v84
	v_exp_f32_e32 v85, v85
	v_mov_b32_e32 v96, 0
	v_mov_b32_e32 v97, 0
	v_add_f32_e32 v84, 1.0, v84
	v_add_f32_e32 v85, 1.0, v85
	v_rcp_f32_e32 v84, v84
	v_rcp_f32_e32 v85, v85
	s_nop 0
	v_pk_fma_f32 v[94:95], v[86:87], v[84:85], v[106:107]
	v_cvt_pk_bf16_f32 v84, v88, v89
	v_cvt_pk_bf16_f32 v85, v90, v91
	v_cvt_pk_bf16_f32 v86, v92, v93
	v_cvt_pk_bf16_f32 v87, v94, v95
	global_store_dwordx4 v[104:105], v[84:87], off offset:256
	v_mov_b32_e32 v90, 0
	v_mov_b32_e32 v94, 0
	v_or_b32_e32 v84, 48, v154
	v_ashrrev_i32_e32 v85, 31, v84
	v_mov_b64_e32 v[86:87], s[18:19]
	v_lshlrev_b64 v[88:89], 11, v[84:85]
	v_mad_i64_i32 v[84:85], s[28:29], v84, s33, v[86:87]
	v_lshl_add_u64 v[92:93], v[152:153], 1, v[84:85]
	s_nop 1
	v_mov_b64_e32 v[84:85], v[208:209]
	v_mov_b64_e32 v[86:87], v[210:211]
	v_lshl_add_u64 v[88:89], s[10:11], 0, v[88:89]
	v_lshl_add_u64 v[88:89], v[152:153], 1, v[88:89]
	v_mov_b32_e32 v95, 0
	s_cbranch_vccnz .LBB0_1764
	s_nop 1
	v_mov_b64_e32 v[102:103], v[224:225]
	v_mov_b64_e32 v[104:105], v[226:227]
	v_lshlrev_b32_e32 v100, 16, v102
	v_and_b32_e32 v101, 0xffff0000, v102
	v_lshlrev_b32_e32 v98, 16, v103
	v_and_b32_e32 v99, 0xffff0000, v103
	v_lshlrev_b32_e32 v96, 16, v104
	v_and_b32_e32 v97, 0xffff0000, v104
	v_lshlrev_b32_e32 v94, 16, v105
	v_and_b32_e32 v95, 0xffff0000, v105
; __device__ __forceinline__ void unpack8(const u32x4 w, float (&f)[8]) { f[0] = bflo(w.x); f[1] = bfhi(w.x); f[2] = bflo(w.y); f[3] = bfhi(w.y); f[4] = bflo(w.z); f[5] = bfhi(w.z); f[6] = bflo(w.w); f[7] = bfhi(w.w); }
; __device__ __forceinline__ u32x4 pack8(const float (&f)[8]) { u32x4 w; w.x = pk2(f[0], f[1]); w.y = pk2(f[2], f[3]); w.z = pk2(f[4], f[5]); w.w = pk2(f[6], f[7]); return w; }
; __device__ __forceinline__ float sigmoidf_(float x) { return __builtin_amdgcn_rcpf(1.0f + __expf(-x)); }
;     __device__ __forceinline__ void operator()(const f32x4 (&acc)[2][2][4][2], const pg8::Unit& u, int wr, int wc, int fr, int fq) const {
;     ...
;         for (int ai = 0; ai < 2; ++ai)
; #pragma unroll
;             for (int m = 0; m < 4; ++m) {
;                 const size_t row = (size_t)(row0 + ai * 128 + m * 16);
; #pragma unroll
;                 for (int bj = 0; bj < 2; ++bj) {
;                     float gt[8], mv[8], o[8];
;                     unpack8(*(const u32x4*)(Z + row * ZW + goff + col0 + bj * 128), gt);
;                     if (!first) unpack8(*(const u32x4*)(Mb + row * D + col0 + bj * 128), mv);
; #pragma unroll
;                     for (int n = 0; n < 2; ++n)
; #pragma unroll
;                         for (int j = 0; j < 4; ++j) o[4 * n + j] = (first ? 0.f : mv[4 * n + j]) + sigmoidf_(gt[4 * n + j]) * acc[ai][bj][m][n][j];
;                     *(u32x4*)(Mb + row * D + col0 + bj * 128) = pack8(o);
.LBB0_1764:
	v_lshlrev_b32_e32 v91, 16, v84
	v_and_b32_e32 v102, 0xffff0000, v84
	v_lshlrev_b32_e32 v103, 16, v85
	v_and_b32_e32 v104, 0xffff0000, v85
	v_mul_f32_e32 v84, 0xbfb8aa3b, v91
	v_mul_f32_e32 v85, 0xbfb8aa3b, v102
	v_exp_f32_e32 v84, v84
	v_exp_f32_e32 v85, v85
	v_lshlrev_b32_e32 v105, 16, v86
	v_and_b32_e32 v86, 0xffff0000, v86
	v_add_f32_e32 v84, 1.0, v84
	v_add_f32_e32 v85, 1.0, v85
	v_rcp_f32_e32 v84, v84
	v_rcp_f32_e32 v85, v85
	v_lshlrev_b32_e32 v106, 16, v87
	v_and_b32_e32 v87, 0xffff0000, v87
	s_and_b64 vcc, exec, s[4:5]
	v_pk_fma_f32 v[80:81], v[80:81], v[84:85], v[100:101]
	v_mul_f32_e32 v84, 0xbfb8aa3b, v103
	v_mul_f32_e32 v85, 0xbfb8aa3b, v104
	v_exp_f32_e32 v84, v84
	v_exp_f32_e32 v85, v85
	v_mov_b32_e32 v91, 0
	v_add_f32_e32 v84, 1.0, v84
	v_add_f32_e32 v85, 1.0, v85
	v_rcp_f32_e32 v84, v84
	v_rcp_f32_e32 v85, v85
	s_nop 0
	v_pk_fma_f32 v[82:83], v[82:83], v[84:85], v[98:99]
	v_mul_f32_e32 v84, 0xbfb8aa3b, v105
	v_mul_f32_e32 v85, 0xbfb8aa3b, v86
	v_exp_f32_e32 v84, v84
	v_exp_f32_e32 v85, v85
	v_add_f32_e32 v84, 1.0, v84
	v_add_f32_e32 v85, 1.0, v85
	v_rcp_f32_e32 v84, v84
	v_rcp_f32_e32 v85, v85
	s_nop 0
	v_pk_fma_f32 v[84:85], v[76:77], v[84:85], v[96:97]
	v_mul_f32_e32 v76, 0xbfb8aa3b, v106
	v_mul_f32_e32 v77, 0xbfb8aa3b, v87
	v_exp_f32_e32 v76, v76
	v_exp_f32_e32 v77, v77
	v_add_f32_e32 v76, 1.0, v76
	v_add_f32_e32 v77, 1.0, v77
	v_rcp_f32_e32 v76, v76
	v_rcp_f32_e32 v77, v77
	s_nop 0
	v_pk_fma_f32 v[86:87], v[78:79], v[76:77], v[94:95]
	v_cvt_pk_bf16_f32 v76, v80, v81
	v_cvt_pk_bf16_f32 v77, v82, v83
	v_cvt_pk_bf16_f32 v78, v84, v85
	v_cvt_pk_bf16_f32 v79, v86, v87
	global_store_dwordx4 v[88:89], v[76:79], off
	s_nop 1
	v_mov_b64_e32 v[76:77], v[212:213]
	v_mov_b64_e32 v[78:79], v[214:215]
	v_mov_b32_e32 v80, 0
	v_mov_b32_e32 v81, 0
	v_mov_b32_e32 v82, 0
	v_mov_b32_e32 v83, 0
	v_mov_b32_e32 v84, 0
	v_mov_b32_e32 v85, 0
	s_cbranch_vccnz .LBB0_1766
	s_nop 1
	v_mov_b64_e32 v[90:91], v[228:229]
	v_mov_b64_e32 v[92:93], v[230:231]
	v_lshlrev_b32_e32 v84, 16, v90
	v_and_b32_e32 v85, 0xffff0000, v90
	v_lshlrev_b32_e32 v82, 16, v91
	v_and_b32_e32 v83, 0xffff0000, v91
	v_lshlrev_b32_e32 v80, 16, v92
	v_and_b32_e32 v81, 0xffff0000, v92
	v_lshlrev_b32_e32 v90, 16, v93
	v_and_b32_e32 v91, 0xffff0000, v93
.LBB0_1766:
	v_lshlrev_b32_e32 v86, 16, v76
	v_and_b32_e32 v87, 0xffff0000, v76
	v_lshlrev_b32_e32 v92, 16, v77
	v_and_b32_e32 v93, 0xffff0000, v77
	v_mul_f32_e32 v76, 0xbfb8aa3b, v86
	v_mul_f32_e32 v77, 0xbfb8aa3b, v87
	v_exp_f32_e32 v76, v76
	v_exp_f32_e32 v77, v77
	v_lshlrev_b32_e32 v94, 16, v78
	v_and_b32_e32 v78, 0xffff0000, v78
	v_add_f32_e32 v76, 1.0, v76
	v_add_f32_e32 v77, 1.0, v77
	v_rcp_f32_e32 v76, v76
	v_rcp_f32_e32 v77, v77
	v_lshlrev_b32_e32 v95, 16, v79
	v_and_b32_e32 v79, 0xffff0000, v79
	s_and_b64 vcc, exec, s[4:5]
	v_pk_fma_f32 v[72:73], v[72:73], v[76:77], v[84:85]
	v_mul_f32_e32 v76, 0xbfb8aa3b, v92
	v_mul_f32_e32 v77, 0xbfb8aa3b, v93
	v_exp_f32_e32 v76, v76
	v_exp_f32_e32 v77, v77
	v_mov_b32_e32 v84, 0
	v_mov_b32_e32 v85, 0
	v_add_f32_e32 v76, 1.0, v76
	v_add_f32_e32 v77, 1.0, v77
	v_rcp_f32_e32 v76, v76
	v_rcp_f32_e32 v77, v77
	s_nop 0
	v_pk_fma_f32 v[74:75], v[74:75], v[76:77], v[82:83]
	v_mul_f32_e32 v76, 0xbfb8aa3b, v94
	v_mul_f32_e32 v77, 0xbfb8aa3b, v78
	v_exp_f32_e32 v76, v76
	v_exp_f32_e32 v77, v77
	v_mov_b32_e32 v82, 0
	v_mov_b32_e32 v83, 0
	v_add_f32_e32 v76, 1.0, v76
	v_add_f32_e32 v77, 1.0, v77
	v_rcp_f32_e32 v76, v76
	v_rcp_f32_e32 v77, v77
	s_nop 0
	v_pk_fma_f32 v[76:77], v[68:69], v[76:77], v[80:81]
	v_mul_f32_e32 v68, 0xbfb8aa3b, v95
	v_mul_f32_e32 v69, 0xbfb8aa3b, v79
	v_exp_f32_e32 v68, v68
	v_exp_f32_e32 v69, v69
	v_mov_b32_e32 v80, 0
	v_mov_b32_e32 v81, 0
	v_add_f32_e32 v68, 1.0, v68
	v_add_f32_e32 v69, 1.0, v69
	v_rcp_f32_e32 v68, v68
	v_rcp_f32_e32 v69, v69
	s_nop 0
	v_pk_fma_f32 v[78:79], v[70:71], v[68:69], v[90:91]
	v_cvt_pk_bf16_f32 v68, v72, v73
	v_cvt_pk_bf16_f32 v69, v74, v75
	v_cvt_pk_bf16_f32 v70, v76, v77
	v_cvt_pk_bf16_f32 v71, v78, v79
	global_store_dwordx4 v[88:89], v[68:71], off offset:256
	v_mov_b32_e32 v74, 0
	v_mov_b32_e32 v78, 0
	v_add_u32_e32 v235, 0x210000, v232
	v_add_u32_e32 v236, 0x252000, v232
	global_load_dwordx4 v[200:203], v235, s[18:19] offset:2048
	global_load_dwordx4 v[204:207], v235, s[18:19] offset:2304
	global_load_dwordx4 v[208:211], v236, s[18:19] offset:2048
	global_load_dwordx4 v[212:215], v236, s[18:19] offset:2304
	s_and_b64 vcc, exec, s[4:5]
	s_cbranch_vccnz .Lem_skip2
	v_add_u32_e32 v235, 0x40000, v233
	v_add_u32_e32 v236, 0x48000, v233
	global_load_dwordx4 v[216:219], v235, s[10:11]
	global_load_dwordx4 v[220:223], v235, s[10:11] offset:256
	global_load_dwordx4 v[224:227], v236, s[10:11]
	global_load_dwordx4 v[228:231], v236, s[10:11] offset:256
.Lem_skip2:
	s_waitcnt vmcnt(0)
	v_add_u32_e32 v68, 0x80, v154
	v_ashrrev_i32_e32 v69, 31, v68
	v_mov_b64_e32 v[70:71], s[18:19]
	v_lshlrev_b64 v[72:73], 11, v[68:69]
	v_mad_i64_i32 v[68:69], s[28:29], v68, s33, v[70:71]
	v_lshl_add_u64 v[76:77], v[152:153], 1, v[68:69]
	s_nop 1
	v_mov_b64_e32 v[68:69], v[200:201]
	v_mov_b64_e32 v[70:71], v[202:203]
	v_lshl_add_u64 v[72:73], s[10:11], 0, v[72:73]
	v_lshl_add_u64 v[72:73], v[152:153], 1, v[72:73]
	v_mov_b32_e32 v79, 0
	s_cbranch_vccnz .LBB0_1768
	s_nop 1
	v_mov_b64_e32 v[86:87], v[216:217]
	v_mov_b64_e32 v[88:89], v[218:219]
	v_lshlrev_b32_e32 v84, 16, v86
	v_and_b32_e32 v85, 0xffff0000, v86
	v_lshlrev_b32_e32 v82, 16, v87
	v_and_b32_e32 v83, 0xffff0000, v87
	v_lshlrev_b32_e32 v80, 16, v88
	v_and_b32_e32 v81, 0xffff0000, v88
	v_lshlrev_b32_e32 v78, 16, v89
	v_and_b32_e32 v79, 0xffff0000, v89
; __device__ __forceinline__ void unpack8(const u32x4 w, float (&f)[8]) { f[0] = bflo(w.x); f[1] = bfhi(w.x); f[2] = bflo(w.y); f[3] = bfhi(w.y); f[4] = bflo(w.z); f[5] = bfhi(w.z); f[6] = bflo(w.w); f[7] = bfhi(w.w); }
; __device__ __forceinline__ u32x4 pack8(const float (&f)[8]) { u32x4 w; w.x = pk2(f[0], f[1]); w.y = pk2(f[2], f[3]); w.z = pk2(f[4], f[5]); w.w = pk2(f[6], f[7]); return w; }
; __device__ __forceinline__ float sigmoidf_(float x) { return __builtin_amdgcn_rcpf(1.0f + __expf(-x)); }
;     __device__ __forceinline__ void operator()(const f32x4 (&acc)[2][2][4][2], const pg8::Unit& u, int wr, int wc, int fr, int fq) const {
;     ...
;                 const size_t row = (size_t)(row0 + ai * 128 + m * 16);
; #pragma unroll
;                 for (int bj = 0; bj < 2; ++bj) {
;                     float gt[8], mv[8], o[8];
;                     unpack8(*(const u32x4*)(Z + row * ZW + goff + col0 + bj * 128), gt);
;                     if (!first) unpack8(*(const u32x4*)(Mb + row * D + col0 + bj * 128), mv);
; #pragma unroll
;                     for (int n = 0; n < 2; ++n)
; #pragma unroll
;                         for (int j = 0; j < 4; ++j) o[4 * n + j] = (first ? 0.f : mv[4 * n + j]) + sigmoidf_(gt[4 * n + j]) * acc[ai][bj][m][n][j];
;                     *(u32x4*)(Mb + row * D + col0 + bj * 128) = pack8(o);
.LBB0_1768:
	v_lshlrev_b32_e32 v75, 16, v68
	v_and_b32_e32 v86, 0xffff0000, v68
	v_lshlrev_b32_e32 v87, 16, v69
	v_and_b32_e32 v88, 0xffff0000, v69
	v_mul_f32_e32 v68, 0xbfb8aa3b, v75
	v_mul_f32_e32 v69, 0xbfb8aa3b, v86
	v_exp_f32_e32 v68, v68
	v_exp_f32_e32 v69, v69
	v_lshlrev_b32_e32 v89, 16, v70
	v_and_b32_e32 v70, 0xffff0000, v70
	v_add_f32_e32 v68, 1.0, v68
	v_add_f32_e32 v69, 1.0, v69
	v_rcp_f32_e32 v68, v68
	v_rcp_f32_e32 v69, v69
	v_lshlrev_b32_e32 v90, 16, v71
	v_and_b32_e32 v71, 0xffff0000, v71
	s_and_b64 vcc, exec, s[4:5]
	v_pk_fma_f32 v[64:65], v[64:65], v[68:69], v[84:85]
	v_mul_f32_e32 v68, 0xbfb8aa3b, v87
	v_mul_f32_e32 v69, 0xbfb8aa3b, v88
	v_exp_f32_e32 v68, v68
	v_exp_f32_e32 v69, v69
	v_mov_b32_e32 v75, 0
	v_add_f32_e32 v68, 1.0, v68
	v_add_f32_e32 v69, 1.0, v69
	v_rcp_f32_e32 v68, v68
	v_rcp_f32_e32 v69, v69
	s_nop 0
	v_pk_fma_f32 v[66:67], v[66:67], v[68:69], v[82:83]
	v_mul_f32_e32 v68, 0xbfb8aa3b, v89
	v_mul_f32_e32 v69, 0xbfb8aa3b, v70
	v_exp_f32_e32 v68, v68
	v_exp_f32_e32 v69, v69
	v_add_f32_e32 v68, 1.0, v68
	v_add_f32_e32 v69, 1.0, v69
	v_rcp_f32_e32 v68, v68
	v_rcp_f32_e32 v69, v69
	s_nop 0
	v_pk_fma_f32 v[68:69], v[60:61], v[68:69], v[80:81]
	v_mul_f32_e32 v60, 0xbfb8aa3b, v90
	v_mul_f32_e32 v61, 0xbfb8aa3b, v71
	v_exp_f32_e32 v60, v60
	v_exp_f32_e32 v61, v61
	v_add_f32_e32 v60, 1.0, v60
	v_add_f32_e32 v61, 1.0, v61
	v_rcp_f32_e32 v60, v60
	v_rcp_f32_e32 v61, v61
	s_nop 0
	v_pk_fma_f32 v[70:71], v[62:63], v[60:61], v[78:79]
	v_cvt_pk_bf16_f32 v60, v64, v65
	v_cvt_pk_bf16_f32 v61, v66, v67
	v_cvt_pk_bf16_f32 v62, v68, v69
	v_cvt_pk_bf16_f32 v63, v70, v71
	global_store_dwordx4 v[72:73], v[60:63], off
	s_nop 1
	v_mov_b64_e32 v[60:61], v[204:205]
	v_mov_b64_e32 v[62:63], v[206:207]
	v_mov_b32_e32 v64, 0
	v_mov_b32_e32 v65, 0
	v_mov_b32_e32 v66, 0
	v_mov_b32_e32 v67, 0
	v_mov_b32_e32 v68, 0
	v_mov_b32_e32 v69, 0
	s_cbranch_vccnz .LBB0_1770
	s_nop 1
	v_mov_b64_e32 v[74:75], v[220:221]
	v_mov_b64_e32 v[76:77], v[222:223]
	v_lshlrev_b32_e32 v68, 16, v74
	v_and_b32_e32 v69, 0xffff0000, v74
	v_lshlrev_b32_e32 v66, 16, v75
	v_and_b32_e32 v67, 0xffff0000, v75
	v_lshlrev_b32_e32 v64, 16, v76
	v_and_b32_e32 v65, 0xffff0000, v76
	v_lshlrev_b32_e32 v74, 16, v77
	v_and_b32_e32 v75, 0xffff0000, v77
.LBB0_1770:
	v_lshlrev_b32_e32 v70, 16, v60
	v_and_b32_e32 v71, 0xffff0000, v60
	v_lshlrev_b32_e32 v76, 16, v61
	v_and_b32_e32 v77, 0xffff0000, v61
	v_mul_f32_e32 v60, 0xbfb8aa3b, v70
	v_mul_f32_e32 v61, 0xbfb8aa3b, v71
	v_exp_f32_e32 v60, v60
	v_exp_f32_e32 v61, v61
	v_lshlrev_b32_e32 v78, 16, v62
	v_and_b32_e32 v62, 0xffff0000, v62
	v_add_f32_e32 v60, 1.0, v60
	v_add_f32_e32 v61, 1.0, v61
	v_rcp_f32_e32 v60, v60
	v_rcp_f32_e32 v61, v61
	v_lshlrev_b32_e32 v79, 16, v63
	v_and_b32_e32 v63, 0xffff0000, v63
	s_and_b64 vcc, exec, s[4:5]
	v_pk_fma_f32 v[56:57], v[56:57], v[60:61], v[68:69]
	v_mul_f32_e32 v60, 0xbfb8aa3b, v76
	v_mul_f32_e32 v61, 0xbfb8aa3b, v77
	v_exp_f32_e32 v60, v60
	v_exp_f32_e32 v61, v61
	v_mov_b32_e32 v68, 0
	v_mov_b32_e32 v69, 0
	v_add_f32_e32 v60, 1.0, v60
	v_add_f32_e32 v61, 1.0, v61
	v_rcp_f32_e32 v60, v60
	v_rcp_f32_e32 v61, v61
	s_nop 0
	v_pk_fma_f32 v[58:59], v[58:59], v[60:61], v[66:67]
	v_mul_f32_e32 v60, 0xbfb8aa3b, v78
	v_mul_f32_e32 v61, 0xbfb8aa3b, v62
	v_exp_f32_e32 v60, v60
	v_exp_f32_e32 v61, v61
	v_mov_b32_e32 v66, 0
	v_mov_b32_e32 v67, 0
	v_add_f32_e32 v60, 1.0, v60
	v_add_f32_e32 v61, 1.0, v61
	v_rcp_f32_e32 v60, v60
	v_rcp_f32_e32 v61, v61
	s_nop 0
	v_pk_fma_f32 v[60:61], v[52:53], v[60:61], v[64:65]
	v_mul_f32_e32 v52, 0xbfb8aa3b, v79
	v_mul_f32_e32 v53, 0xbfb8aa3b, v63
	v_exp_f32_e32 v52, v52
	v_exp_f32_e32 v53, v53
	v_mov_b32_e32 v64, 0
	v_mov_b32_e32 v65, 0
	v_add_f32_e32 v52, 1.0, v52
	v_add_f32_e32 v53, 1.0, v53
	v_rcp_f32_e32 v52, v52
	v_rcp_f32_e32 v53, v53
	s_nop 0
	v_pk_fma_f32 v[62:63], v[54:55], v[52:53], v[74:75]
	v_cvt_pk_bf16_f32 v52, v56, v57
	v_cvt_pk_bf16_f32 v53, v58, v59
	v_cvt_pk_bf16_f32 v54, v60, v61
	v_cvt_pk_bf16_f32 v55, v62, v63
	global_store_dwordx4 v[72:73], v[52:55], off offset:256
	v_mov_b32_e32 v58, 0
	v_mov_b32_e32 v62, 0
	v_add_u32_e32 v52, 0x90, v154
	v_ashrrev_i32_e32 v53, 31, v52
	v_mov_b64_e32 v[54:55], s[18:19]
	v_lshlrev_b64 v[56:57], 11, v[52:53]
	v_mad_i64_i32 v[52:53], s[28:29], v52, s33, v[54:55]
	v_lshl_add_u64 v[60:61], v[152:153], 1, v[52:53]
	s_nop 1
	v_mov_b64_e32 v[52:53], v[208:209]
	v_mov_b64_e32 v[54:55], v[210:211]
	v_lshl_add_u64 v[56:57], s[10:11], 0, v[56:57]
	v_lshl_add_u64 v[56:57], v[152:153], 1, v[56:57]
	v_mov_b32_e32 v63, 0
	s_cbranch_vccnz .LBB0_1772
	s_nop 1
	v_mov_b64_e32 v[70:71], v[224:225]
	v_mov_b64_e32 v[72:73], v[226:227]
	v_lshlrev_b32_e32 v68, 16, v70
	v_and_b32_e32 v69, 0xffff0000, v70
	v_lshlrev_b32_e32 v66, 16, v71
	v_and_b32_e32 v67, 0xffff0000, v71
	v_lshlrev_b32_e32 v64, 16, v72
	v_and_b32_e32 v65, 0xffff0000, v72
	v_lshlrev_b32_e32 v62, 16, v73
	v_and_b32_e32 v63, 0xffff0000, v73
; __device__ __forceinline__ void unpack8(const u32x4 w, float (&f)[8]) { f[0] = bflo(w.x); f[1] = bfhi(w.x); f[2] = bflo(w.y); f[3] = bfhi(w.y); f[4] = bflo(w.z); f[5] = bfhi(w.z); f[6] = bflo(w.w); f[7] = bfhi(w.w); }
; __device__ __forceinline__ u32x4 pack8(const float (&f)[8]) { u32x4 w; w.x = pk2(f[0], f[1]); w.y = pk2(f[2], f[3]); w.z = pk2(f[4], f[5]); w.w = pk2(f[6], f[7]); return w; }
; __device__ __forceinline__ float sigmoidf_(float x) { return __builtin_amdgcn_rcpf(1.0f + __expf(-x)); }
;     __device__ __forceinline__ void operator()(const f32x4 (&acc)[2][2][4][2], const pg8::Unit& u, int wr, int wc, int fr, int fq) const {
;     ...
;                 const size_t row = (size_t)(row0 + ai * 128 + m * 16);
; #pragma unroll
;                 for (int bj = 0; bj < 2; ++bj) {
;                     float gt[8], mv[8], o[8];
;                     unpack8(*(const u32x4*)(Z + row * ZW + goff + col0 + bj * 128), gt);
;                     if (!first) unpack8(*(const u32x4*)(Mb + row * D + col0 + bj * 128), mv);
; #pragma unroll
;                     for (int n = 0; n < 2; ++n)
; #pragma unroll
;                         for (int j = 0; j < 4; ++j) o[4 * n + j] = (first ? 0.f : mv[4 * n + j]) + sigmoidf_(gt[4 * n + j]) * acc[ai][bj][m][n][j];
;                     *(u32x4*)(Mb + row * D + col0 + bj * 128) = pack8(o);
.LBB0_1772:
	v_lshlrev_b32_e32 v59, 16, v52
	v_and_b32_e32 v70, 0xffff0000, v52
	v_lshlrev_b32_e32 v71, 16, v53
	v_and_b32_e32 v72, 0xffff0000, v53
	v_mul_f32_e32 v52, 0xbfb8aa3b, v59
	v_mul_f32_e32 v53, 0xbfb8aa3b, v70
	v_exp_f32_e32 v52, v52
	v_exp_f32_e32 v53, v53
	v_lshlrev_b32_e32 v73, 16, v54
	v_and_b32_e32 v54, 0xffff0000, v54
	v_add_f32_e32 v52, 1.0, v52
	v_add_f32_e32 v53, 1.0, v53
	v_rcp_f32_e32 v52, v52
	v_rcp_f32_e32 v53, v53
	v_lshlrev_b32_e32 v74, 16, v55
	v_and_b32_e32 v55, 0xffff0000, v55
	s_and_b64 vcc, exec, s[4:5]
	v_pk_fma_f32 v[48:49], v[48:49], v[52:53], v[68:69]
	v_mul_f32_e32 v52, 0xbfb8aa3b, v71
	v_mul_f32_e32 v53, 0xbfb8aa3b, v72
	v_exp_f32_e32 v52, v52
	v_exp_f32_e32 v53, v53
	v_mov_b32_e32 v59, 0
	v_add_f32_e32 v52, 1.0, v52
	v_add_f32_e32 v53, 1.0, v53
	v_rcp_f32_e32 v52, v52
	v_rcp_f32_e32 v53, v53
	s_nop 0
	v_pk_fma_f32 v[50:51], v[50:51], v[52:53], v[66:67]
	v_mul_f32_e32 v52, 0xbfb8aa3b, v73
	v_mul_f32_e32 v53, 0xbfb8aa3b, v54
	v_exp_f32_e32 v52, v52
	v_exp_f32_e32 v53, v53
	v_add_f32_e32 v52, 1.0, v52
	v_add_f32_e32 v53, 1.0, v53
	v_rcp_f32_e32 v52, v52
	v_rcp_f32_e32 v53, v53
	s_nop 0
	v_pk_fma_f32 v[52:53], v[44:45], v[52:53], v[64:65]
	v_mul_f32_e32 v44, 0xbfb8aa3b, v74
	v_mul_f32_e32 v45, 0xbfb8aa3b, v55
	v_exp_f32_e32 v44, v44
	v_exp_f32_e32 v45, v45
	v_add_f32_e32 v44, 1.0, v44
	v_add_f32_e32 v45, 1.0, v45
	v_rcp_f32_e32 v44, v44
	v_rcp_f32_e32 v45, v45
	s_nop 0
	v_pk_fma_f32 v[54:55], v[46:47], v[44:45], v[62:63]
	v_cvt_pk_bf16_f32 v44, v48, v49
	v_cvt_pk_bf16_f32 v45, v50, v51
	v_cvt_pk_bf16_f32 v46, v52, v53
	v_cvt_pk_bf16_f32 v47, v54, v55
	global_store_dwordx4 v[56:57], v[44:47], off
	s_nop 1
	v_mov_b64_e32 v[44:45], v[212:213]
	v_mov_b64_e32 v[46:47], v[214:215]
	v_mov_b32_e32 v48, 0
	v_mov_b32_e32 v49, 0
	v_mov_b32_e32 v50, 0
	v_mov_b32_e32 v51, 0
	v_mov_b32_e32 v52, 0
	v_mov_b32_e32 v53, 0
	s_cbranch_vccnz .LBB0_1774
	s_nop 1
	v_mov_b64_e32 v[58:59], v[228:229]
	v_mov_b64_e32 v[60:61], v[230:231]
	v_lshlrev_b32_e32 v52, 16, v58
	v_and_b32_e32 v53, 0xffff0000, v58
	v_lshlrev_b32_e32 v50, 16, v59
	v_and_b32_e32 v51, 0xffff0000, v59
	v_lshlrev_b32_e32 v48, 16, v60
	v_and_b32_e32 v49, 0xffff0000, v60
	v_lshlrev_b32_e32 v58, 16, v61
	v_and_b32_e32 v59, 0xffff0000, v61
.LBB0_1774:
	v_lshlrev_b32_e32 v54, 16, v44
	v_and_b32_e32 v55, 0xffff0000, v44
	v_lshlrev_b32_e32 v60, 16, v45
	v_and_b32_e32 v61, 0xffff0000, v45
	v_mul_f32_e32 v44, 0xbfb8aa3b, v54
	v_mul_f32_e32 v45, 0xbfb8aa3b, v55
	v_exp_f32_e32 v44, v44
	v_exp_f32_e32 v45, v45
	v_lshlrev_b32_e32 v62, 16, v46
	v_and_b32_e32 v46, 0xffff0000, v46
	v_add_f32_e32 v44, 1.0, v44
	v_add_f32_e32 v45, 1.0, v45
	v_rcp_f32_e32 v44, v44
	v_rcp_f32_e32 v45, v45
	v_lshlrev_b32_e32 v63, 16, v47
	v_and_b32_e32 v47, 0xffff0000, v47
	s_and_b64 vcc, exec, s[4:5]
	v_pk_fma_f32 v[40:41], v[40:41], v[44:45], v[52:53]
	v_mul_f32_e32 v44, 0xbfb8aa3b, v60
	v_mul_f32_e32 v45, 0xbfb8aa3b, v61
	v_exp_f32_e32 v44, v44
	v_exp_f32_e32 v45, v45
	v_mov_b32_e32 v52, 0
	v_mov_b32_e32 v53, 0
	v_add_f32_e32 v44, 1.0, v44
	v_add_f32_e32 v45, 1.0, v45
	v_rcp_f32_e32 v44, v44
	v_rcp_f32_e32 v45, v45
	s_nop 0
	v_pk_fma_f32 v[42:43], v[42:43], v[44:45], v[50:51]
	v_mul_f32_e32 v44, 0xbfb8aa3b, v62
	v_mul_f32_e32 v45, 0xbfb8aa3b, v46
	v_exp_f32_e32 v44, v44
	v_exp_f32_e32 v45, v45
	v_mov_b32_e32 v50, 0
	v_mov_b32_e32 v51, 0
	v_add_f32_e32 v44, 1.0, v44
	v_add_f32_e32 v45, 1.0, v45
	v_rcp_f32_e32 v44, v44
	v_rcp_f32_e32 v45, v45
	s_nop 0
	v_pk_fma_f32 v[44:45], v[36:37], v[44:45], v[48:49]
	v_mul_f32_e32 v36, 0xbfb8aa3b, v63
	v_mul_f32_e32 v37, 0xbfb8aa3b, v47
	v_exp_f32_e32 v36, v36
	v_exp_f32_e32 v37, v37
	v_mov_b32_e32 v48, 0
	v_mov_b32_e32 v49, 0
	v_add_f32_e32 v36, 1.0, v36
	v_add_f32_e32 v37, 1.0, v37
	v_rcp_f32_e32 v36, v36
	v_rcp_f32_e32 v37, v37
	s_nop 0
	v_pk_fma_f32 v[46:47], v[38:39], v[36:37], v[58:59]
	v_cvt_pk_bf16_f32 v36, v40, v41
	v_cvt_pk_bf16_f32 v37, v42, v43
	v_cvt_pk_bf16_f32 v38, v44, v45
	v_cvt_pk_bf16_f32 v39, v46, v47
	global_store_dwordx4 v[56:57], v[36:39], off offset:256
	v_mov_b32_e32 v42, 0
	v_mov_b32_e32 v46, 0
	v_add_u32_e32 v235, 0x294000, v232
	v_add_u32_e32 v236, 0x2d6000, v232
	global_load_dwordx4 v[200:203], v235, s[18:19] offset:2048
	global_load_dwordx4 v[204:207], v235, s[18:19] offset:2304
	global_load_dwordx4 v[208:211], v236, s[18:19] offset:2048
	global_load_dwordx4 v[212:215], v236, s[18:19] offset:2304
	s_and_b64 vcc, exec, s[4:5]
	s_cbranch_vccnz .Lem_skip3
	v_add_u32_e32 v235, 0x50000, v233
	v_add_u32_e32 v236, 0x58000, v233
	global_load_dwordx4 v[216:219], v235, s[10:11]
	global_load_dwordx4 v[220:223], v235, s[10:11] offset:256
	global_load_dwordx4 v[224:227], v236, s[10:11]
	global_load_dwordx4 v[228:231], v236, s[10:11] offset:256
.Lem_skip3:
	s_waitcnt vmcnt(0)
	v_add_u32_e32 v36, 0xa0, v154
	v_ashrrev_i32_e32 v37, 31, v36
	v_mov_b64_e32 v[38:39], s[18:19]
	v_lshlrev_b64 v[40:41], 11, v[36:37]
	v_mad_i64_i32 v[36:37], s[28:29], v36, s33, v[38:39]
	v_lshl_add_u64 v[44:45], v[152:153], 1, v[36:37]
	s_nop 1
	v_mov_b64_e32 v[36:37], v[200:201]
	v_mov_b64_e32 v[38:39], v[202:203]
	v_lshl_add_u64 v[40:41], s[10:11], 0, v[40:41]
	v_lshl_add_u64 v[40:41], v[152:153], 1, v[40:41]
	v_mov_b32_e32 v47, 0
	s_cbranch_vccnz .LBB0_1776
	s_nop 1
	v_mov_b64_e32 v[54:55], v[216:217]
	v_mov_b64_e32 v[56:57], v[218:219]
	v_lshlrev_b32_e32 v52, 16, v54
	v_and_b32_e32 v53, 0xffff0000, v54
	v_lshlrev_b32_e32 v50, 16, v55
	v_and_b32_e32 v51, 0xffff0000, v55
	v_lshlrev_b32_e32 v48, 16, v56
	v_and_b32_e32 v49, 0xffff0000, v56
	v_lshlrev_b32_e32 v46, 16, v57
	v_and_b32_e32 v47, 0xffff0000, v57
; __device__ __forceinline__ void unpack8(const u32x4 w, float (&f)[8]) { f[0] = bflo(w.x); f[1] = bfhi(w.x); f[2] = bflo(w.y); f[3] = bfhi(w.y); f[4] = bflo(w.z); f[5] = bfhi(w.z); f[6] = bflo(w.w); f[7] = bfhi(w.w); }
; __device__ __forceinline__ u32x4 pack8(const float (&f)[8]) { u32x4 w; w.x = pk2(f[0], f[1]); w.y = pk2(f[2], f[3]); w.z = pk2(f[4], f[5]); w.w = pk2(f[6], f[7]); return w; }
; __device__ __forceinline__ float sigmoidf_(float x) { return __builtin_amdgcn_rcpf(1.0f + __expf(-x)); }
;     __device__ __forceinline__ void operator()(const f32x4 (&acc)[2][2][4][2], const pg8::Unit& u, int wr, int wc, int fr, int fq) const {
;     ...
;                 const size_t row = (size_t)(row0 + ai * 128 + m * 16);
; #pragma unroll
;                 for (int bj = 0; bj < 2; ++bj) {
;                     float gt[8], mv[8], o[8];
;                     unpack8(*(const u32x4*)(Z + row * ZW + goff + col0 + bj * 128), gt);
;                     if (!first) unpack8(*(const u32x4*)(Mb + row * D + col0 + bj * 128), mv);
; #pragma unroll
;                     for (int n = 0; n < 2; ++n)
; #pragma unroll
;                         for (int j = 0; j < 4; ++j) o[4 * n + j] = (first ? 0.f : mv[4 * n + j]) + sigmoidf_(gt[4 * n + j]) * acc[ai][bj][m][n][j];
;                     *(u32x4*)(Mb + row * D + col0 + bj * 128) = pack8(o);
.LBB0_1776:
	v_lshlrev_b32_e32 v43, 16, v36
	v_and_b32_e32 v54, 0xffff0000, v36
	v_lshlrev_b32_e32 v55, 16, v37
	v_and_b32_e32 v56, 0xffff0000, v37
	v_mul_f32_e32 v36, 0xbfb8aa3b, v43
	v_mul_f32_e32 v37, 0xbfb8aa3b, v54
	v_exp_f32_e32 v36, v36
	v_exp_f32_e32 v37, v37
	v_lshlrev_b32_e32 v57, 16, v38
	v_and_b32_e32 v38, 0xffff0000, v38
	v_add_f32_e32 v36, 1.0, v36
	v_add_f32_e32 v37, 1.0, v37
	v_rcp_f32_e32 v36, v36
	v_rcp_f32_e32 v37, v37
	v_lshlrev_b32_e32 v58, 16, v39
	v_and_b32_e32 v39, 0xffff0000, v39
	s_and_b64 vcc, exec, s[4:5]
	v_pk_fma_f32 v[32:33], v[32:33], v[36:37], v[52:53]
	v_mul_f32_e32 v36, 0xbfb8aa3b, v55
	v_mul_f32_e32 v37, 0xbfb8aa3b, v56
	v_exp_f32_e32 v36, v36
	v_exp_f32_e32 v37, v37
	v_mov_b32_e32 v43, 0
	v_add_f32_e32 v36, 1.0, v36
	v_add_f32_e32 v37, 1.0, v37
	v_rcp_f32_e32 v36, v36
	v_rcp_f32_e32 v37, v37
	s_nop 0
	v_pk_fma_f32 v[34:35], v[34:35], v[36:37], v[50:51]
	v_mul_f32_e32 v36, 0xbfb8aa3b, v57
	v_mul_f32_e32 v37, 0xbfb8aa3b, v38
	v_exp_f32_e32 v36, v36
	v_exp_f32_e32 v37, v37
	v_add_f32_e32 v36, 1.0, v36
	v_add_f32_e32 v37, 1.0, v37
	v_rcp_f32_e32 v36, v36
	v_rcp_f32_e32 v37, v37
	s_nop 0
	v_pk_fma_f32 v[36:37], v[24:25], v[36:37], v[48:49]
	v_mul_f32_e32 v24, 0xbfb8aa3b, v58
	v_mul_f32_e32 v25, 0xbfb8aa3b, v39
	v_exp_f32_e32 v24, v24
	v_exp_f32_e32 v25, v25
	v_add_f32_e32 v24, 1.0, v24
	v_add_f32_e32 v25, 1.0, v25
	v_rcp_f32_e32 v24, v24
	v_rcp_f32_e32 v25, v25
	s_nop 0
	v_pk_fma_f32 v[38:39], v[26:27], v[24:25], v[46:47]
	v_cvt_pk_bf16_f32 v24, v32, v33
	v_cvt_pk_bf16_f32 v25, v34, v35
	v_cvt_pk_bf16_f32 v26, v36, v37
	v_cvt_pk_bf16_f32 v27, v38, v39
	global_store_dwordx4 v[40:41], v[24:27], off
	s_nop 1
	v_mov_b64_e32 v[24:25], v[204:205]
	v_mov_b64_e32 v[26:27], v[206:207]
	v_mov_b32_e32 v32, 0
	v_mov_b32_e32 v33, 0
	v_mov_b32_e32 v34, 0
	v_mov_b32_e32 v35, 0
	v_mov_b32_e32 v36, 0
	v_mov_b32_e32 v37, 0
	s_cbranch_vccnz .LBB0_1778
	s_nop 1
	v_mov_b64_e32 v[42:43], v[220:221]
	v_mov_b64_e32 v[44:45], v[222:223]
	v_lshlrev_b32_e32 v36, 16, v42
	v_and_b32_e32 v37, 0xffff0000, v42
	v_lshlrev_b32_e32 v34, 16, v43
	v_and_b32_e32 v35, 0xffff0000, v43
	v_lshlrev_b32_e32 v32, 16, v44
	v_and_b32_e32 v33, 0xffff0000, v44
	v_lshlrev_b32_e32 v42, 16, v45
	v_and_b32_e32 v43, 0xffff0000, v45
; __device__ __forceinline__ void unpack8(const u32x4 w, float (&f)[8]) { f[0] = bflo(w.x); f[1] = bfhi(w.x); f[2] = bflo(w.y); f[3] = bfhi(w.y); f[4] = bflo(w.z); f[5] = bfhi(w.z); f[6] = bflo(w.w); f[7] = bfhi(w.w); }
; __device__ __forceinline__ u32x4 pack8(const float (&f)[8]) { u32x4 w; w.x = pk2(f[0], f[1]); w.y = pk2(f[2], f[3]); w.z = pk2(f[4], f[5]); w.w = pk2(f[6], f[7]); return w; }
; __device__ __forceinline__ float sigmoidf_(float x) { return __builtin_amdgcn_rcpf(1.0f + __expf(-x)); }
; template <class Epi, class Sched>
; __device__ __forceinline__ void gemm_phase(PG8_LAS unsigned char* lds, const Gemm g, const Sched& S, const Epi& E, const int tid_in) {
;     ...
;         cur = nxt; cA = nA; cB = nB; ++ui;
;     __device__ __forceinline__ void operator()(const f32x4 (&acc)[2][2][4][2], const pg8::Unit& u, int wr, int wc, int fr, int fq) const {
;     ...
;                 const size_t row = (size_t)(row0 + ai * 128 + m * 16);
; #pragma unroll
;                 for (int bj = 0; bj < 2; ++bj) {
;                     float gt[8], mv[8], o[8];
;                     unpack8(*(const u32x4*)(Z + row * ZW + goff + col0 + bj * 128), gt);
;                     if (!first) unpack8(*(const u32x4*)(Mb + row * D + col0 + bj * 128), mv);
; #pragma unroll
;                     for (int n = 0; n < 2; ++n)
; #pragma unroll
;                         for (int j = 0; j < 4; ++j) o[4 * n + j] = (first ? 0.f : mv[4 * n + j]) + sigmoidf_(gt[4 * n + j]) * acc[ai][bj][m][n][j];
;                     *(u32x4*)(Mb + row * D + col0 + bj * 128) = pack8(o);
.LBB0_1778:
	v_lshlrev_b32_e32 v38, 16, v24
	v_and_b32_e32 v39, 0xffff0000, v24
	v_lshlrev_b32_e32 v44, 16, v25
	v_and_b32_e32 v45, 0xffff0000, v25
	v_mul_f32_e32 v24, 0xbfb8aa3b, v38
	v_mul_f32_e32 v25, 0xbfb8aa3b, v39
	v_exp_f32_e32 v24, v24
	v_exp_f32_e32 v25, v25
	v_lshlrev_b32_e32 v46, 16, v26
	v_and_b32_e32 v26, 0xffff0000, v26
	v_add_f32_e32 v24, 1.0, v24
	v_add_f32_e32 v25, 1.0, v25
	v_rcp_f32_e32 v24, v24
	v_rcp_f32_e32 v25, v25
	v_lshlrev_b32_e32 v47, 16, v27
	v_and_b32_e32 v27, 0xffff0000, v27
	s_and_b64 vcc, exec, s[4:5]
	v_pk_fma_f32 v[20:21], v[20:21], v[24:25], v[36:37]
	v_mul_f32_e32 v24, 0xbfb8aa3b, v44
	v_mul_f32_e32 v25, 0xbfb8aa3b, v45
	v_exp_f32_e32 v24, v24
	v_exp_f32_e32 v25, v25
	v_mov_b32_e32 v36, 0
	v_mov_b32_e32 v37, 0
	v_add_f32_e32 v24, 1.0, v24
	v_add_f32_e32 v25, 1.0, v25
	v_rcp_f32_e32 v24, v24
	v_rcp_f32_e32 v25, v25
	s_nop 0
	v_pk_fma_f32 v[22:23], v[22:23], v[24:25], v[34:35]
	v_mul_f32_e32 v24, 0xbfb8aa3b, v46
	v_mul_f32_e32 v25, 0xbfb8aa3b, v26
	v_exp_f32_e32 v24, v24
	v_exp_f32_e32 v25, v25
	v_mov_b32_e32 v34, 0
	v_mov_b32_e32 v35, 0
	v_add_f32_e32 v24, 1.0, v24
	v_add_f32_e32 v25, 1.0, v25
	v_rcp_f32_e32 v24, v24
	v_rcp_f32_e32 v25, v25
	s_nop 0
	v_pk_fma_f32 v[24:25], v[16:17], v[24:25], v[32:33]
	v_mul_f32_e32 v16, 0xbfb8aa3b, v47
	v_mul_f32_e32 v17, 0xbfb8aa3b, v27
	v_exp_f32_e32 v16, v16
	v_exp_f32_e32 v17, v17
	v_mov_b32_e32 v32, 0
	v_mov_b32_e32 v33, 0
	v_add_f32_e32 v16, 1.0, v16
	v_add_f32_e32 v17, 1.0, v17
	v_rcp_f32_e32 v16, v16
	v_rcp_f32_e32 v17, v17
	s_nop 0
	v_pk_fma_f32 v[26:27], v[18:19], v[16:17], v[42:43]
	v_cvt_pk_bf16_f32 v16, v20, v21
	v_cvt_pk_bf16_f32 v17, v22, v23
	v_cvt_pk_bf16_f32 v18, v24, v25
	v_cvt_pk_bf16_f32 v19, v26, v27
	global_store_dwordx4 v[40:41], v[16:19], off offset:256
	v_mov_b32_e32 v22, 0
	v_mov_b32_e32 v26, 0
	v_add_u32_e32 v16, 0xb0, v154
	v_ashrrev_i32_e32 v17, 31, v16
	v_mov_b64_e32 v[18:19], s[18:19]
	v_lshlrev_b64 v[20:21], 11, v[16:17]
	v_mad_i64_i32 v[16:17], s[28:29], v16, s33, v[18:19]
	v_lshl_add_u64 v[24:25], v[152:153], 1, v[16:17]
	s_nop 1
	v_mov_b64_e32 v[16:17], v[208:209]
	v_mov_b64_e32 v[18:19], v[210:211]
	v_lshl_add_u64 v[20:21], s[10:11], 0, v[20:21]
	v_lshl_add_u64 v[20:21], v[152:153], 1, v[20:21]
	v_mov_b32_e32 v27, 0
	s_cbranch_vccnz .LBB0_1780
	s_nop 1
	v_mov_b64_e32 v[38:39], v[224:225]
	v_mov_b64_e32 v[40:41], v[226:227]
	v_lshlrev_b32_e32 v36, 16, v38
	v_and_b32_e32 v37, 0xffff0000, v38
	v_lshlrev_b32_e32 v34, 16, v39
	v_and_b32_e32 v35, 0xffff0000, v39
	v_lshlrev_b32_e32 v32, 16, v40
	v_and_b32_e32 v33, 0xffff0000, v40
	v_lshlrev_b32_e32 v26, 16, v41
	v_and_b32_e32 v27, 0xffff0000, v41
.LBB0_1780:
	v_lshlrev_b32_e32 v23, 16, v16
	v_and_b32_e32 v38, 0xffff0000, v16
	v_lshlrev_b32_e32 v39, 16, v17
	v_and_b32_e32 v40, 0xffff0000, v17
	v_mul_f32_e32 v16, 0xbfb8aa3b, v23
	v_mul_f32_e32 v17, 0xbfb8aa3b, v38
	v_exp_f32_e32 v16, v16
	v_exp_f32_e32 v17, v17
	v_lshlrev_b32_e32 v41, 16, v18
	v_and_b32_e32 v18, 0xffff0000, v18
	v_add_f32_e32 v16, 1.0, v16
	v_add_f32_e32 v17, 1.0, v17
	v_rcp_f32_e32 v16, v16
	v_rcp_f32_e32 v17, v17
	v_lshlrev_b32_e32 v42, 16, v19
	v_and_b32_e32 v19, 0xffff0000, v19
	s_and_b64 vcc, exec, s[4:5]
	v_pk_fma_f32 v[12:13], v[12:13], v[16:17], v[36:37]
	v_mul_f32_e32 v16, 0xbfb8aa3b, v39
	v_mul_f32_e32 v17, 0xbfb8aa3b, v40
	v_exp_f32_e32 v16, v16
	v_exp_f32_e32 v17, v17
	v_mov_b32_e32 v23, 0
	v_add_f32_e32 v16, 1.0, v16
	v_add_f32_e32 v17, 1.0, v17
	v_rcp_f32_e32 v16, v16
	v_rcp_f32_e32 v17, v17
	s_nop 0
	v_pk_fma_f32 v[14:15], v[14:15], v[16:17], v[34:35]
	v_mul_f32_e32 v16, 0xbfb8aa3b, v41
	v_mul_f32_e32 v17, 0xbfb8aa3b, v18
	v_exp_f32_e32 v16, v16
	v_exp_f32_e32 v17, v17
	v_add_f32_e32 v16, 1.0, v16
	v_add_f32_e32 v17, 1.0, v17
	v_rcp_f32_e32 v16, v16
	v_rcp_f32_e32 v17, v17
	s_nop 0
	v_pk_fma_f32 v[16:17], v[8:9], v[16:17], v[32:33]
	v_mul_f32_e32 v8, 0xbfb8aa3b, v42
	v_mul_f32_e32 v9, 0xbfb8aa3b, v19
	v_exp_f32_e32 v8, v8
	v_exp_f32_e32 v9, v9
	v_add_f32_e32 v8, 1.0, v8
	v_add_f32_e32 v9, 1.0, v9
	v_rcp_f32_e32 v8, v8
	v_rcp_f32_e32 v9, v9
	s_nop 0
	v_pk_fma_f32 v[18:19], v[10:11], v[8:9], v[26:27]
	v_cvt_pk_bf16_f32 v8, v12, v13
	v_cvt_pk_bf16_f32 v9, v14, v15
	v_cvt_pk_bf16_f32 v10, v16, v17
	v_cvt_pk_bf16_f32 v11, v18, v19
	global_store_dwordx4 v[20:21], v[8:11], off
	s_nop 1
	v_mov_b64_e32 v[8:9], v[212:213]
	v_mov_b64_e32 v[10:11], v[214:215]
	v_mov_b32_e32 v12, 0
	v_mov_b32_e32 v13, 0
	v_mov_b32_e32 v14, 0
	v_mov_b32_e32 v15, 0
	v_mov_b32_e32 v16, 0
	v_mov_b32_e32 v17, 0
	s_cbranch_vccnz .LBB0_1739
	s_nop 1
	v_mov_b64_e32 v[22:23], v[228:229]
	v_mov_b64_e32 v[24:25], v[230:231]
	v_lshlrev_b32_e32 v16, 16, v22
	v_and_b32_e32 v17, 0xffff0000, v22
	v_lshlrev_b32_e32 v14, 16, v23
	v_and_b32_e32 v15, 0xffff0000, v23
	v_lshlrev_b32_e32 v12, 16, v24
	v_and_b32_e32 v13, 0xffff0000, v24
	v_lshlrev_b32_e32 v22, 16, v25
	v_and_b32_e32 v23, 0xffff0000, v25
	s_branch .LBB0_1739

; #define PG8_STAGE(bufoff, gbase, voff) do { _Pragma("unroll") for (int _i = 0; _i < 2; ++_i) \
;         __builtin_amdgcn_global_load_lds((const unsigned*)((const char*)(gbase) + (voff)[_i]), (PG8_LAS unsigned*)(lds + (bufoff) + ldsw + _i * 8192), 16, 0, 0); } while (0)
; #define PG8_LDA(dst, b, h) do { _Pragma("unroll") for (int m = 0; m < 4; ++m) _Pragma("unroll") for (int k = 0; k < 2; ++k) dst[m][k] = *(const PG8_LAS bf16x8*)(lds + PG8_SA(b, h) + aoff + m * 2048 + k * 1024); } while (0)
; #define PG8_LDB(dst, b, h) do { _Pragma("unroll") for (int n = 0; n < 2; ++n) _Pragma("unroll") for (int k = 0; k < 2; ++k) dst[n][k] = *(const PG8_LAS bf16x8*)(lds + PG8_SB(b, h) + boff + n * 2048 + k * 1024); } while (0)
; #define PG8_MMA(ai, bj, At, Bt) do { __builtin_amdgcn_s_setprio(1); _Pragma("unroll") for (int m = 0; m < 4; ++m) _Pragma("unroll") for (int n = 0; n < 2; ++n) _Pragma("unroll") for (int k = 0; k < 2; ++k) \
;         acc[ai][bj][m][n] = __builtin_amdgcn_mfma_f32_16x16x32_bf16(Bt[n][k], At[m][k], acc[ai][bj][m][n], 0, 0, 0); __builtin_amdgcn_s_setprio(0); } while (0)
; #define PG8_WAIT_V(n) asm volatile("s_waitcnt vmcnt(" #n ")" ::: "memory")
; #define PG8_WAIT_L(n) asm volatile("s_waitcnt lgkmcnt(" #n ")" ::: "memory")
; template <class Epi, class Sched>
; __device__ __forceinline__ void gemm_phase(PG8_LAS unsigned char* lds, const Gemm g, const Sched& S, const Epi& E, const int tid_in) {
;     ...
;             PG8_LDB(B0, 0, 0); PG8_SCHED; PG8_LDA(At, 0, 0); PG8_STAGE(PG8_SA(1, 1), a1 + hstepA, voffA);
;             PG8_WAIT_L(8); PG8_BAR; PG8_WAIT_L(0); PG8_MMA(0, 0, At, B0); PG8_BAR; PG8_SCHED;
;             PG8_LDB(B1, 0, 1); PG8_STAGE(PG8_SB(0, 0), b2, voffB);
;             PG8_BAR; PG8_WAIT_L(0); PG8_MMA(0, 1, At, B1); PG8_BAR;
;             PG8_LDA(At, 0, 1); PG8_STAGE(PG8_SA(0, 0), a2, voffA);
;             PG8_BAR; PG8_WAIT_L(0); PG8_MMA(1, 0, At, B0); PG8_BAR; PG8_SCHED;
;             PG8_STAGE(PG8_SB(0, 1), b2 + hstepB, voffB);
;             PG8_WAIT_V(6); PG8_BAR; PG8_MMA(1, 1, At, B1); PG8_BAR;
;             PG8_LDB(B0, 1, 0); PG8_SCHED; PG8_LDA(At, 1, 0); PG8_STAGE(PG8_SA(0, 1), a2 + hstepA, voffA);
;             PG8_WAIT_L(8); PG8_BAR; PG8_WAIT_L(0); PG8_MMA(0, 0, At, B0); PG8_BAR; PG8_SCHED;
;             PG8_LDB(B1, 1, 1); PG8_STAGE(PG8_SB(1, 0), b3, voffB);
;             PG8_BAR; PG8_WAIT_L(0); PG8_MMA(0, 1, At, B1); PG8_BAR;
.LBB0_1897:
	v_add_u32_e32 v136, s15, v151
	ds_read_b128 v[144:147], v136
	ds_read_b128 v[154:157], v136 offset:1024
	ds_read_b128 v[158:161], v136 offset:2048
	ds_read_b128 v[184:187], v136 offset:3072
	s_add_u32 s18, s16, 0xfffc0080
	s_addc_u32 s19, s17, -1
	s_cmp_eq_u32 s57, 12
	s_cselect_b32 s21, s9, s19
	s_cselect_b32 s20, s53, s18
	s_cselect_b32 s19, s7, s56
	s_cselect_b32 s18, s54, s55
	v_lshl_add_u64 v[136:137], s[16:17], 0, v[132:133]
	s_add_i32 m0, s35, 0xc000
	ds_read_b128 v[188:191], v153
	ds_read_b128 v[192:195], v153 offset:1024
	ds_read_b128 v[196:199], v153 offset:2048
	ds_read_b128 v[200:203], v153 offset:3072
	ds_read_b128 v[204:207], v153 offset:4096
	ds_read_b128 v[208:211], v153 offset:5120
	ds_read_b128 v[212:215], v153 offset:6144
	ds_read_b128 v[216:219], v153 offset:7168
	global_load_lds_dwordx4 v[136:137], off
	v_lshl_add_u64 v[136:137], s[16:17], 0, v[134:135]
	s_add_i32 m0, s35, 0xe000
	s_nop 0
	global_load_lds_dwordx4 v[136:137], off
	s_waitcnt lgkmcnt(8)
	s_barrier
	s_waitcnt lgkmcnt(0)
	s_setprio 1
	s_waitcnt lgkmcnt(0)
	v_mfma_f32_16x16x32_bf16 v[128:131], v[144:147], v[188:191], v[128:131]
	v_mfma_f32_16x16x32_bf16 v[124:127], v[158:161], v[188:191], v[124:127]
	v_mfma_f32_16x16x32_bf16 v[112:115], v[144:147], v[196:199], v[112:115]
	v_mfma_f32_16x16x32_bf16 v[108:111], v[158:161], v[196:199], v[108:111]
	v_mfma_f32_16x16x32_bf16 v[96:99], v[144:147], v[204:207], v[96:99]
	v_mfma_f32_16x16x32_bf16 v[92:95], v[158:161], v[204:207], v[92:95]
	v_mfma_f32_16x16x32_bf16 v[80:83], v[144:147], v[212:215], v[80:83]
	v_mfma_f32_16x16x32_bf16 v[76:79], v[158:161], v[212:215], v[76:79]
	v_mfma_f32_16x16x32_bf16 v[128:131], v[154:157], v[192:195], v[128:131]
	v_mfma_f32_16x16x32_bf16 v[124:127], v[184:187], v[192:195], v[124:127]
	v_mfma_f32_16x16x32_bf16 v[112:115], v[154:157], v[200:203], v[112:115]
	v_mfma_f32_16x16x32_bf16 v[108:111], v[184:187], v[200:203], v[108:111]
	v_mfma_f32_16x16x32_bf16 v[96:99], v[154:157], v[208:211], v[96:99]
	v_mfma_f32_16x16x32_bf16 v[92:95], v[184:187], v[208:211], v[92:95]
	v_mfma_f32_16x16x32_bf16 v[80:83], v[154:157], v[216:219], v[80:83]
	v_mfma_f32_16x16x32_bf16 v[76:79], v[184:187], v[216:219], v[76:79]
	s_setprio 0
	s_barrier
	v_add_u32_e32 v136, s37, v151
	s_mov_b32 m0, s31
	ds_read_b128 v[220:223], v136
	ds_read_b128 v[224:227], v136 offset:1024
	ds_read_b128 v[228:231], v136 offset:2048
	ds_read_b128 v[232:235], v136 offset:3072
	v_lshl_add_u64 v[136:137], s[18:19], 0, v[30:31]
	global_load_lds_dwordx4 v[136:137], off
	v_lshl_add_u64 v[138:139], s[18:19], 0, v[28:29]
	s_mov_b32 m0, s34
	s_nop 0
	global_load_lds_dwordx4 v[138:139], off
	s_barrier
	s_waitcnt lgkmcnt(0)
	s_setprio 1
	s_waitcnt lgkmcnt(0)
	v_mfma_f32_16x16x32_bf16 v[120:123], v[220:223], v[188:191], v[120:123]
	v_mfma_f32_16x16x32_bf16 v[116:119], v[228:231], v[188:191], v[116:119]
	v_mfma_f32_16x16x32_bf16 v[104:107], v[220:223], v[196:199], v[104:107]
	v_mfma_f32_16x16x32_bf16 v[100:103], v[228:231], v[196:199], v[100:103]
	v_mfma_f32_16x16x32_bf16 v[88:91], v[220:223], v[204:207], v[88:91]
	v_mfma_f32_16x16x32_bf16 v[84:87], v[228:231], v[204:207], v[84:87]
	v_mfma_f32_16x16x32_bf16 v[72:75], v[220:223], v[212:215], v[72:75]
	v_mfma_f32_16x16x32_bf16 v[68:71], v[228:231], v[212:215], v[68:71]
	v_mfma_f32_16x16x32_bf16 v[120:123], v[224:227], v[192:195], v[120:123]
	v_mfma_f32_16x16x32_bf16 v[116:119], v[232:235], v[192:195], v[116:119]
	v_mfma_f32_16x16x32_bf16 v[104:107], v[224:227], v[200:203], v[104:107]
	v_mfma_f32_16x16x32_bf16 v[100:103], v[232:235], v[200:203], v[100:103]
	v_mfma_f32_16x16x32_bf16 v[88:91], v[224:227], v[208:211], v[88:91]
	v_mfma_f32_16x16x32_bf16 v[84:87], v[232:235], v[208:211], v[84:87]
	v_mfma_f32_16x16x32_bf16 v[72:75], v[224:227], v[216:219], v[72:75]
	v_mfma_f32_16x16x32_bf16 v[68:71], v[232:235], v[216:219], v[68:71]
	s_setprio 0
	s_mov_b32 m0, s35
	v_lshl_add_u64 v[148:149], s[20:21], 0, v[30:31]
	s_barrier
	ds_read_b128 v[188:191], v153 offset:16384
	ds_read_b128 v[192:195], v153 offset:17408
	ds_read_b128 v[196:199], v153 offset:18432
	ds_read_b128 v[200:203], v153 offset:19456
	ds_read_b128 v[204:207], v153 offset:20480
	ds_read_b128 v[208:211], v153 offset:21504
	ds_read_b128 v[212:215], v153 offset:22528
	ds_read_b128 v[216:219], v153 offset:23552
	global_load_lds_dwordx4 v[148:149], off
	v_lshl_add_u64 v[236:237], s[20:21], 0, v[28:29]
	s_mov_b32 m0, s36
	s_nop 0
	global_load_lds_dwordx4 v[236:237], off
	s_barrier
	s_waitcnt lgkmcnt(0)
	s_setprio 1
	s_waitcnt lgkmcnt(0)
	v_mfma_f32_16x16x32_bf16 v[64:67], v[144:147], v[188:191], v[64:67]
	v_mfma_f32_16x16x32_bf16 v[60:63], v[158:161], v[188:191], v[60:63]
	v_mfma_f32_16x16x32_bf16 v[48:51], v[144:147], v[196:199], v[48:51]
	v_mfma_f32_16x16x32_bf16 v[44:47], v[158:161], v[196:199], v[44:47]
	v_mfma_f32_16x16x32_bf16 v[32:35], v[144:147], v[204:207], v[32:35]
	v_mfma_f32_16x16x32_bf16 v[24:27], v[158:161], v[204:207], v[24:27]
	v_mfma_f32_16x16x32_bf16 v[12:15], v[144:147], v[212:215], v[12:15]
	v_mfma_f32_16x16x32_bf16 v[8:11], v[158:161], v[212:215], v[8:11]
	v_mfma_f32_16x16x32_bf16 v[64:67], v[154:157], v[192:195], v[64:67]
	v_mfma_f32_16x16x32_bf16 v[60:63], v[184:187], v[192:195], v[60:63]
	v_mfma_f32_16x16x32_bf16 v[48:51], v[154:157], v[200:203], v[48:51]
	v_mfma_f32_16x16x32_bf16 v[44:47], v[184:187], v[200:203], v[44:47]
	v_mfma_f32_16x16x32_bf16 v[32:35], v[154:157], v[208:211], v[32:35]
	v_mfma_f32_16x16x32_bf16 v[24:27], v[184:187], v[208:211], v[24:27]
	v_mfma_f32_16x16x32_bf16 v[12:15], v[154:157], v[216:219], v[12:15]
	v_mfma_f32_16x16x32_bf16 v[8:11], v[184:187], v[216:219], v[8:11]
	s_setprio 0
	s_barrier
; #define PG8_STAGE(bufoff, gbase, voff) do { _Pragma("unroll") for (int _i = 0; _i < 2; ++_i) \
;         __builtin_amdgcn_global_load_lds((const unsigned*)((const char*)(gbase) + (voff)[_i]), (PG8_LAS unsigned*)(lds + (bufoff) + ldsw + _i * 8192), 16, 0, 0); } while (0)
; #define PG8_LDA(dst, b, h) do { _Pragma("unroll") for (int m = 0; m < 4; ++m) _Pragma("unroll") for (int k = 0; k < 2; ++k) dst[m][k] = *(const PG8_LAS bf16x8*)(lds + PG8_SA(b, h) + aoff + m * 2048 + k * 1024); } while (0)
; #define PG8_LDB(dst, b, h) do { _Pragma("unroll") for (int n = 0; n < 2; ++n) _Pragma("unroll") for (int k = 0; k < 2; ++k) dst[n][k] = *(const PG8_LAS bf16x8*)(lds + PG8_SB(b, h) + boff + n * 2048 + k * 1024); } while (0)
; #define PG8_MMA(ai, bj, At, Bt) do { __builtin_amdgcn_s_setprio(1); _Pragma("unroll") for (int m = 0; m < 4; ++m) _Pragma("unroll") for (int n = 0; n < 2; ++n) _Pragma("unroll") for (int k = 0; k < 2; ++k) \
;         acc[ai][bj][m][n] = __builtin_amdgcn_mfma_f32_16x16x32_bf16(Bt[n][k], At[m][k], acc[ai][bj][m][n], 0, 0, 0); __builtin_amdgcn_s_setprio(0); } while (0)
; #define PG8_WAIT_V(n) asm volatile("s_waitcnt vmcnt(" #n ")" ::: "memory")
; #define PG8_WAIT_L(n) asm volatile("s_waitcnt lgkmcnt(" #n ")" ::: "memory")
; #define PG8_BAR __builtin_amdgcn_s_barrier()
; #define PG8_SCHED __builtin_amdgcn_sched_barrier(0)
; template <class Epi, class Sched>
; __device__ __forceinline__ void gemm_phase(PG8_LAS unsigned char* lds, const Gemm g, const Sched& S, const Epi& E, const int tid_in) {
;     ...
;             PG8_STAGE(PG8_SB(0, 1), b2 + hstepB, voffB);
;             PG8_WAIT_V(6); PG8_BAR; PG8_MMA(1, 1, At, B1); PG8_BAR;
;             PG8_LDB(B0, 1, 0); PG8_SCHED; PG8_LDA(At, 1, 0); PG8_STAGE(PG8_SA(0, 1), a2 + hstepA, voffA);
;             PG8_WAIT_L(8); PG8_BAR; PG8_WAIT_L(0); PG8_MMA(0, 0, At, B0); PG8_BAR; PG8_SCHED;
;             PG8_LDB(B1, 1, 1); PG8_STAGE(PG8_SB(1, 0), b3, voffB);
;             PG8_BAR; PG8_WAIT_L(0); PG8_MMA(0, 1, At, B1); PG8_BAR;
;             PG8_LDA(At, 1, 1); PG8_STAGE(PG8_SA(1, 0), a3, voffA);
;             PG8_BAR; PG8_WAIT_L(0); PG8_MMA(1, 0, At, B0); PG8_BAR; PG8_SCHED;
	s_add_u32 s58, s18, 0x40000
	s_addc_u32 s59, s19, 0
	s_mov_b32 m0, s38
	v_lshl_add_u64 v[144:145], s[58:59], 0, v[30:31]
	global_load_lds_dwordx4 v[144:145], off
	v_lshl_add_u64 v[144:145], s[58:59], 0, v[28:29]
	s_mov_b32 m0, s39
	s_nop 0
	global_load_lds_dwordx4 v[144:145], off
	s_waitcnt vmcnt(6)
	s_barrier
	s_setprio 1
	v_mfma_f32_16x16x32_bf16 v[56:59], v[220:223], v[188:191], v[56:59]
	v_mfma_f32_16x16x32_bf16 v[52:55], v[228:231], v[188:191], v[52:55]
	v_mfma_f32_16x16x32_bf16 v[40:43], v[220:223], v[196:199], v[40:43]
	v_mfma_f32_16x16x32_bf16 v[36:39], v[228:231], v[196:199], v[36:39]
	v_mfma_f32_16x16x32_bf16 v[20:23], v[220:223], v[204:207], v[20:23]
	v_mfma_f32_16x16x32_bf16 v[16:19], v[228:231], v[204:207], v[16:19]
	v_mfma_f32_16x16x32_bf16 v[4:7], v[220:223], v[212:215], v[4:7]
	v_mfma_f32_16x16x32_bf16 v[0:3], v[228:231], v[212:215], v[0:3]
	v_mfma_f32_16x16x32_bf16 v[56:59], v[224:227], v[192:195], v[56:59]
	v_mfma_f32_16x16x32_bf16 v[52:55], v[232:235], v[192:195], v[52:55]
	v_mfma_f32_16x16x32_bf16 v[40:43], v[224:227], v[200:203], v[40:43]
	v_mfma_f32_16x16x32_bf16 v[36:39], v[232:235], v[200:203], v[36:39]
	v_mfma_f32_16x16x32_bf16 v[20:23], v[224:227], v[208:211], v[20:23]
	v_mfma_f32_16x16x32_bf16 v[16:19], v[232:235], v[208:211], v[16:19]
	v_mfma_f32_16x16x32_bf16 v[4:7], v[224:227], v[216:219], v[4:7]
	v_mfma_f32_16x16x32_bf16 v[0:3], v[232:235], v[216:219], v[0:3]
	s_setprio 0
	v_add_u32_e32 v184, s42, v151
	s_barrier
	ds_read_b128 v[144:147], v184
	ds_read_b128 v[154:157], v184 offset:1024
	ds_read_b128 v[158:161], v184 offset:2048
	ds_read_b128 v[184:187], v184 offset:3072
	s_add_u32 s20, s20, 0x40000
	s_addc_u32 s21, s21, 0
	s_mov_b32 m0, s40
	v_lshl_add_u64 v[220:221], s[20:21], 0, v[30:31]
	ds_read_b128 v[188:191], v153 offset:32768
	ds_read_b128 v[192:195], v153 offset:33792
	ds_read_b128 v[196:199], v153 offset:34816
	ds_read_b128 v[200:203], v153 offset:35840
	ds_read_b128 v[204:207], v153 offset:36864
	ds_read_b128 v[208:211], v153 offset:37888
	ds_read_b128 v[212:215], v153 offset:38912
	ds_read_b128 v[216:219], v153 offset:39936
	global_load_lds_dwordx4 v[220:221], off
	v_lshl_add_u64 v[220:221], s[20:21], 0, v[28:29]
	s_mov_b32 m0, s41
	s_nop 0
	global_load_lds_dwordx4 v[220:221], off
	s_waitcnt lgkmcnt(8)
	s_barrier
	s_waitcnt lgkmcnt(0)
	s_setprio 1
	s_waitcnt lgkmcnt(0)
	v_mfma_f32_16x16x32_bf16 v[128:131], v[144:147], v[188:191], v[128:131]
	v_mfma_f32_16x16x32_bf16 v[124:127], v[158:161], v[188:191], v[124:127]
	v_mfma_f32_16x16x32_bf16 v[112:115], v[144:147], v[196:199], v[112:115]
	v_mfma_f32_16x16x32_bf16 v[108:111], v[158:161], v[196:199], v[108:111]
	v_mfma_f32_16x16x32_bf16 v[96:99], v[144:147], v[204:207], v[96:99]
	v_mfma_f32_16x16x32_bf16 v[92:95], v[158:161], v[204:207], v[92:95]
	v_mfma_f32_16x16x32_bf16 v[80:83], v[144:147], v[212:215], v[80:83]
	v_mfma_f32_16x16x32_bf16 v[76:79], v[158:161], v[212:215], v[76:79]
	v_mfma_f32_16x16x32_bf16 v[128:131], v[154:157], v[192:195], v[128:131]
	v_mfma_f32_16x16x32_bf16 v[124:127], v[184:187], v[192:195], v[124:127]
	v_mfma_f32_16x16x32_bf16 v[112:115], v[154:157], v[200:203], v[112:115]
	v_mfma_f32_16x16x32_bf16 v[108:111], v[184:187], v[200:203], v[108:111]
	v_mfma_f32_16x16x32_bf16 v[96:99], v[154:157], v[208:211], v[96:99]
	v_mfma_f32_16x16x32_bf16 v[92:95], v[184:187], v[208:211], v[92:95]
	v_mfma_f32_16x16x32_bf16 v[80:83], v[154:157], v[216:219], v[80:83]
	v_mfma_f32_16x16x32_bf16 v[76:79], v[184:187], v[216:219], v[76:79]
	s_setprio 0
	s_barrier
	s_mov_b32 m0, s43
	v_add_u32_e32 v232, s47, v151
	v_lshl_add_u64 v[136:137], v[136:137], 0, s[94:95]
	ds_read_b128 v[220:223], v232
	ds_read_b128 v[224:227], v232 offset:1024
	ds_read_b128 v[228:231], v232 offset:2048
	ds_read_b128 v[232:235], v232 offset:3072
	global_load_lds_dwordx4 v[136:137], off
	v_lshl_add_u64 v[136:137], v[138:139], 0, s[94:95]
	s_mov_b32 m0, s44
	s_nop 0
	global_load_lds_dwordx4 v[136:137], off
	s_barrier
	s_waitcnt lgkmcnt(0)
	s_setprio 1
	s_waitcnt lgkmcnt(0)
	v_mfma_f32_16x16x32_bf16 v[120:123], v[220:223], v[188:191], v[120:123]
	v_mfma_f32_16x16x32_bf16 v[116:119], v[228:231], v[188:191], v[116:119]
	v_mfma_f32_16x16x32_bf16 v[104:107], v[220:223], v[196:199], v[104:107]
	v_mfma_f32_16x16x32_bf16 v[100:103], v[228:231], v[196:199], v[100:103]
	v_mfma_f32_16x16x32_bf16 v[88:91], v[220:223], v[204:207], v[88:91]
	v_mfma_f32_16x16x32_bf16 v[84:87], v[228:231], v[204:207], v[84:87]
	v_mfma_f32_16x16x32_bf16 v[72:75], v[220:223], v[212:215], v[72:75]
	v_mfma_f32_16x16x32_bf16 v[68:71], v[228:231], v[212:215], v[68:71]
	v_mfma_f32_16x16x32_bf16 v[120:123], v[224:227], v[192:195], v[120:123]
	v_mfma_f32_16x16x32_bf16 v[116:119], v[232:235], v[192:195], v[116:119]
	v_mfma_f32_16x16x32_bf16 v[104:107], v[224:227], v[200:203], v[104:107]
	v_mfma_f32_16x16x32_bf16 v[100:103], v[232:235], v[200:203], v[100:103]
	v_mfma_f32_16x16x32_bf16 v[88:91], v[224:227], v[208:211], v[88:91]
	v_mfma_f32_16x16x32_bf16 v[84:87], v[232:235], v[208:211], v[84:87]
	v_mfma_f32_16x16x32_bf16 v[72:75], v[224:227], v[216:219], v[72:75]
	v_mfma_f32_16x16x32_bf16 v[68:71], v[232:235], v[216:219], v[68:71]
	s_setprio 0
	s_mov_b32 m0, s45
	v_lshl_add_u64 v[136:137], v[148:149], 0, s[94:95]
	s_barrier
	ds_read_b128 v[188:191], v153 offset:49152
	ds_read_b128 v[192:195], v153 offset:50176
	ds_read_b128 v[196:199], v153 offset:51200
	ds_read_b128 v[200:203], v153 offset:52224
	ds_read_b128 v[204:207], v153 offset:53248
	ds_read_b128 v[208:211], v153 offset:54272
	ds_read_b128 v[212:215], v153 offset:55296
	ds_read_b128 v[216:219], v153 offset:56320
	global_load_lds_dwordx4 v[136:137], off
	v_lshl_add_u64 v[136:137], v[236:237], 0, s[94:95]
	s_mov_b32 m0, s46
	s_nop 0
	global_load_lds_dwordx4 v[136:137], off
	s_barrier
; #define PG8_MMA(ai, bj, At, Bt) do { __builtin_amdgcn_s_setprio(1); _Pragma("unroll") for (int m = 0; m < 4; ++m) _Pragma("unroll") for (int n = 0; n < 2; ++n) _Pragma("unroll") for (int k = 0; k < 2; ++k) \
;         acc[ai][bj][m][n] = __builtin_amdgcn_mfma_f32_16x16x32_bf16(Bt[n][k], At[m][k], acc[ai][bj][m][n], 0, 0, 0); __builtin_amdgcn_s_setprio(0); } while (0)
; #define PG8_WAIT_V(n) asm volatile("s_waitcnt vmcnt(" #n ")" ::: "memory")
; #define PG8_BAR __builtin_amdgcn_s_barrier()
; #define X (outg(c))
; template <class Epi, class Sched>
; __device__ __forceinline__ void gemm_phase(PG8_LAS unsigned char* lds, const Gemm g, const Sched& S, const Epi& E, const int tid_in) {
;     ...
;             PG8_WAIT_V(6); PG8_BAR; PG8_MMA(1, 1, At, B1); PG8_BAR;
;     __device__ __forceinline__ void operator()(const f32x4 (&acc)[2][2][4][2], const pg8::Unit& u, int wr, int wc, int fr, int fq) const {
;         const int row0 = u.pm * 256 + wr * 64 + fr, col0 = u.pn * 256 + wc * 32 + 4 * fq;
; #pragma unroll
;         for (int ai = 0; ai < 2; ++ai)
; #pragma unroll
;             for (int m = 0; m < 4; ++m) {
;                 const size_t off = (size_t)(row0 + ai * 128 + m * 16) * D + col0;
; #pragma unroll
;                 for (int bj = 0; bj < 2; ++bj)
; #pragma unroll
;                     for (int n = 0; n < 2; ++n) { const f32x4 r = *(const f32x4*)(Xin + off + bj * 128 + n * 16); *(f32x4*)(X + off + bj * 128 + n * 16) = r + acc[ai][bj][m][n] * s; }
	s_waitcnt lgkmcnt(0)
	s_setprio 1
	s_waitcnt lgkmcnt(0)
	v_mfma_f32_16x16x32_bf16 v[64:67], v[144:147], v[188:191], v[64:67]
	v_mfma_f32_16x16x32_bf16 v[60:63], v[158:161], v[188:191], v[60:63]
	v_mfma_f32_16x16x32_bf16 v[48:51], v[144:147], v[196:199], v[48:51]
	v_mfma_f32_16x16x32_bf16 v[44:47], v[158:161], v[196:199], v[44:47]
	v_mfma_f32_16x16x32_bf16 v[32:35], v[144:147], v[204:207], v[32:35]
	v_mfma_f32_16x16x32_bf16 v[24:27], v[158:161], v[204:207], v[24:27]
	v_mfma_f32_16x16x32_bf16 v[12:15], v[144:147], v[212:215], v[12:15]
	v_mfma_f32_16x16x32_bf16 v[8:11], v[158:161], v[212:215], v[8:11]
	v_mfma_f32_16x16x32_bf16 v[64:67], v[154:157], v[192:195], v[64:67]
	v_mfma_f32_16x16x32_bf16 v[60:63], v[184:187], v[192:195], v[60:63]
	v_mfma_f32_16x16x32_bf16 v[48:51], v[154:157], v[200:203], v[48:51]
	v_mfma_f32_16x16x32_bf16 v[44:47], v[184:187], v[200:203], v[44:47]
	v_mfma_f32_16x16x32_bf16 v[32:35], v[154:157], v[208:211], v[32:35]
	v_mfma_f32_16x16x32_bf16 v[24:27], v[184:187], v[208:211], v[24:27]
	v_mfma_f32_16x16x32_bf16 v[12:15], v[154:157], v[216:219], v[12:15]
	v_mfma_f32_16x16x32_bf16 v[8:11], v[184:187], v[216:219], v[8:11]
	s_setprio 0
	s_barrier
	s_add_u32 s18, s18, 0x40080
	s_addc_u32 s19, s19, 0
	s_mov_b32 m0, s48
	v_lshl_add_u64 v[136:137], s[18:19], 0, v[30:31]
	global_load_lds_dwordx4 v[136:137], off
	v_lshl_add_u64 v[136:137], s[18:19], 0, v[28:29]
	s_mov_b32 m0, s49
	s_nop 0
	global_load_lds_dwordx4 v[136:137], off
	s_waitcnt vmcnt(6)
	s_barrier
	s_setprio 1
	v_mfma_f32_16x16x32_bf16 v[56:59], v[220:223], v[188:191], v[56:59]
	v_mfma_f32_16x16x32_bf16 v[52:55], v[228:231], v[188:191], v[52:55]
	v_mfma_f32_16x16x32_bf16 v[40:43], v[220:223], v[196:199], v[40:43]
	v_mfma_f32_16x16x32_bf16 v[36:39], v[228:231], v[196:199], v[36:39]
	v_mfma_f32_16x16x32_bf16 v[20:23], v[220:223], v[204:207], v[20:23]
	v_mfma_f32_16x16x32_bf16 v[16:19], v[228:231], v[204:207], v[16:19]
	v_mfma_f32_16x16x32_bf16 v[4:7], v[220:223], v[212:215], v[4:7]
	v_mfma_f32_16x16x32_bf16 v[0:3], v[228:231], v[212:215], v[0:3]
	v_mfma_f32_16x16x32_bf16 v[56:59], v[224:227], v[192:195], v[56:59]
	v_mfma_f32_16x16x32_bf16 v[52:55], v[232:235], v[192:195], v[52:55]
	v_mfma_f32_16x16x32_bf16 v[40:43], v[224:227], v[200:203], v[40:43]
	v_mfma_f32_16x16x32_bf16 v[36:39], v[232:235], v[200:203], v[36:39]
	v_mfma_f32_16x16x32_bf16 v[20:23], v[224:227], v[208:211], v[20:23]
	v_mfma_f32_16x16x32_bf16 v[16:19], v[232:235], v[208:211], v[16:19]
	v_mfma_f32_16x16x32_bf16 v[4:7], v[224:227], v[216:219], v[4:7]
	v_mfma_f32_16x16x32_bf16 v[0:3], v[232:235], v[216:219], v[0:3]
	s_setprio 0
	s_add_i32 s57, s57, 2
	s_add_u32 s16, s16, 0x100
	s_addc_u32 s17, s17, 0
	s_add_u32 s55, s55, 0x100
	s_addc_u32 s56, s56, 0
	s_cmp_gt_u32 s57, 13
	s_barrier
	s_cbranch_scc0 .LBB0_1897
	v_lshl_add_u32 v148, s14, 8, v150
	v_lshl_or_b32 v149, s52, 8, v152
	v_lshlrev_b32_e32 v149, 2, v149
	v_lshl_add_u32 v149, v148, 12, v149
	v_mov_b32_e32 v136, v149
	v_add_u32_e32 v137, 0x10000, v149
	v_add_u32_e32 v138, 0x20000, v149
	v_add_u32_e32 v139, 0x30000, v149
	v_add_u32_e32 v236, 0x80000, v149
	v_add_u32_e32 v237, 0x90000, v149
	v_add_u32_e32 v238, 0xa0000, v149
	v_add_u32_e32 v239, 0xb0000, v149
	global_load_dwordx4 v[184:187], v136, s[4:5]
	global_load_dwordx4 v[188:191], v136, s[4:5] offset:64
	global_load_dwordx4 v[192:195], v136, s[4:5] offset:512
	global_load_dwordx4 v[196:199], v136, s[4:5] offset:576
	global_load_dwordx4 v[200:203], v137, s[4:5]
	global_load_dwordx4 v[204:207], v137, s[4:5] offset:64
	global_load_dwordx4 v[208:211], v137, s[4:5] offset:512
	global_load_dwordx4 v[212:215], v137, s[4:5] offset:576
	global_load_dwordx4 v[216:219], v138, s[4:5]
	global_load_dwordx4 v[220:223], v138, s[4:5] offset:64
	global_load_dwordx4 v[224:227], v138, s[4:5] offset:512
	global_load_dwordx4 v[228:231], v138, s[4:5] offset:576
	global_load_dwordx4 v[232:235], v139, s[4:5]
	global_load_dwordx4 v[154:157], v139, s[4:5] offset:64
	global_load_dwordx4 v[158:161], v139, s[4:5] offset:512
	global_load_dwordx4 v[144:147], v139, s[4:5] offset:576
	s_waitcnt vmcnt(15)
	v_pk_add_f32 v[130:131], v[130:131], v[186:187]
	v_pk_add_f32 v[128:129], v[128:129], v[184:185]
	global_store_dwordx4 v136, v[128:131], s[4:5]
	s_waitcnt vmcnt(15)
	v_pk_add_f32 v[126:127], v[126:127], v[190:191]
	v_pk_add_f32 v[124:125], v[124:125], v[188:189]
	global_store_dwordx4 v136, v[124:127], s[4:5] offset:64
	s_waitcnt vmcnt(15)
	v_pk_add_f32 v[122:123], v[122:123], v[194:195]
	v_pk_add_f32 v[120:121], v[120:121], v[192:193]
	global_store_dwordx4 v136, v[120:123], s[4:5] offset:512
	s_waitcnt vmcnt(15)
	v_pk_add_f32 v[118:119], v[118:119], v[198:199]
	v_pk_add_f32 v[116:117], v[116:117], v[196:197]
	global_store_dwordx4 v136, v[116:119], s[4:5] offset:576
	s_waitcnt vmcnt(15)
	v_pk_add_f32 v[114:115], v[114:115], v[202:203]
	v_pk_add_f32 v[112:113], v[112:113], v[200:201]
	global_store_dwordx4 v137, v[112:115], s[4:5]
	s_waitcnt vmcnt(15)
	v_pk_add_f32 v[110:111], v[110:111], v[206:207]
	v_pk_add_f32 v[108:109], v[108:109], v[204:205]
	global_store_dwordx4 v137, v[108:111], s[4:5] offset:64
	s_waitcnt vmcnt(15)
	v_pk_add_f32 v[106:107], v[106:107], v[210:211]
	v_pk_add_f32 v[104:105], v[104:105], v[208:209]
	global_store_dwordx4 v137, v[104:107], s[4:5] offset:512
	s_waitcnt vmcnt(15)
; #define X (outg(c))
; template <class Epi, class Sched>
; __device__ __forceinline__ void gemm_phase(PG8_LAS unsigned char* lds, const Gemm g, const Sched& S, const Epi& E, const int tid_in) {
;     ...
;         cur = nxt; cA = nA; cB = nB; ++ui;
;     __device__ __forceinline__ void operator()(const f32x4 (&acc)[2][2][4][2], const pg8::Unit& u, int wr, int wc, int fr, int fq) const {
;     ...
;             for (int m = 0; m < 4; ++m) {
;                 const size_t off = (size_t)(row0 + ai * 128 + m * 16) * D + col0;
; #pragma unroll
;                 for (int bj = 0; bj < 2; ++bj)
; #pragma unroll
;                     for (int n = 0; n < 2; ++n) { const f32x4 r = *(const f32x4*)(Xin + off + bj * 128 + n * 16); *(f32x4*)(X + off + bj * 128 + n * 16) = r + acc[ai][bj][m][n] * s; }
	v_pk_add_f32 v[102:103], v[102:103], v[214:215]
	v_pk_add_f32 v[100:101], v[100:101], v[212:213]
	global_store_dwordx4 v137, v[100:103], s[4:5] offset:576
	s_waitcnt vmcnt(15)
	v_pk_add_f32 v[98:99], v[98:99], v[218:219]
	v_pk_add_f32 v[96:97], v[96:97], v[216:217]
	global_store_dwordx4 v138, v[96:99], s[4:5]
	s_waitcnt vmcnt(15)
	v_pk_add_f32 v[94:95], v[94:95], v[222:223]
	v_pk_add_f32 v[92:93], v[92:93], v[220:221]
	global_store_dwordx4 v138, v[92:95], s[4:5] offset:64
	s_waitcnt vmcnt(15)
	v_pk_add_f32 v[90:91], v[90:91], v[226:227]
	v_pk_add_f32 v[88:89], v[88:89], v[224:225]
	global_store_dwordx4 v138, v[88:91], s[4:5] offset:512
	s_waitcnt vmcnt(15)
	v_pk_add_f32 v[86:87], v[86:87], v[230:231]
	v_pk_add_f32 v[84:85], v[84:85], v[228:229]
	global_store_dwordx4 v138, v[84:87], s[4:5] offset:576
	s_waitcnt vmcnt(15)
	v_pk_add_f32 v[82:83], v[82:83], v[234:235]
	v_pk_add_f32 v[80:81], v[80:81], v[232:233]
	global_store_dwordx4 v139, v[80:83], s[4:5]
	s_waitcnt vmcnt(15)
	v_pk_add_f32 v[78:79], v[78:79], v[156:157]
	v_pk_add_f32 v[76:77], v[76:77], v[154:155]
	global_store_dwordx4 v139, v[76:79], s[4:5] offset:64
	s_waitcnt vmcnt(15)
	v_pk_add_f32 v[74:75], v[74:75], v[160:161]
	v_pk_add_f32 v[72:73], v[72:73], v[158:159]
	global_store_dwordx4 v139, v[72:75], s[4:5] offset:512
	s_waitcnt vmcnt(15)
	v_pk_add_f32 v[70:71], v[70:71], v[146:147]
	v_pk_add_f32 v[68:69], v[68:69], v[144:145]
	global_store_dwordx4 v139, v[68:71], s[4:5] offset:576
	global_load_dwordx4 v[184:187], v236, s[4:5]
	global_load_dwordx4 v[188:191], v236, s[4:5] offset:64
	global_load_dwordx4 v[192:195], v236, s[4:5] offset:512
	global_load_dwordx4 v[196:199], v236, s[4:5] offset:576
	global_load_dwordx4 v[200:203], v237, s[4:5]
	global_load_dwordx4 v[204:207], v237, s[4:5] offset:64
	global_load_dwordx4 v[208:211], v237, s[4:5] offset:512
	global_load_dwordx4 v[212:215], v237, s[4:5] offset:576
	global_load_dwordx4 v[216:219], v238, s[4:5]
	global_load_dwordx4 v[220:223], v238, s[4:5] offset:64
	global_load_dwordx4 v[224:227], v238, s[4:5] offset:512
	global_load_dwordx4 v[228:231], v238, s[4:5] offset:576
	global_load_dwordx4 v[232:235], v239, s[4:5]
	global_load_dwordx4 v[154:157], v239, s[4:5] offset:64
	global_load_dwordx4 v[158:161], v239, s[4:5] offset:512
	global_load_dwordx4 v[144:147], v239, s[4:5] offset:576
	s_waitcnt vmcnt(15)
	v_pk_add_f32 v[66:67], v[66:67], v[186:187]
	v_pk_add_f32 v[64:65], v[64:65], v[184:185]
	global_store_dwordx4 v236, v[64:67], s[4:5]
	s_waitcnt vmcnt(15)
	v_pk_add_f32 v[62:63], v[62:63], v[190:191]
	v_pk_add_f32 v[60:61], v[60:61], v[188:189]
	global_store_dwordx4 v236, v[60:63], s[4:5] offset:64
	s_waitcnt vmcnt(15)
	v_pk_add_f32 v[58:59], v[58:59], v[194:195]
	v_pk_add_f32 v[56:57], v[56:57], v[192:193]
	global_store_dwordx4 v236, v[56:59], s[4:5] offset:512
	s_waitcnt vmcnt(15)
	v_pk_add_f32 v[54:55], v[54:55], v[198:199]
	v_pk_add_f32 v[52:53], v[52:53], v[196:197]
	global_store_dwordx4 v236, v[52:55], s[4:5] offset:576
	s_waitcnt vmcnt(15)
	v_pk_add_f32 v[50:51], v[50:51], v[202:203]
	v_pk_add_f32 v[48:49], v[48:49], v[200:201]
	global_store_dwordx4 v237, v[48:51], s[4:5]
	s_waitcnt vmcnt(15)
	v_pk_add_f32 v[46:47], v[46:47], v[206:207]
	v_pk_add_f32 v[44:45], v[44:45], v[204:205]
	global_store_dwordx4 v237, v[44:47], s[4:5] offset:64
	s_waitcnt vmcnt(15)
	v_pk_add_f32 v[42:43], v[42:43], v[210:211]
	v_pk_add_f32 v[40:41], v[40:41], v[208:209]
	global_store_dwordx4 v237, v[40:43], s[4:5] offset:512
	s_waitcnt vmcnt(15)
	v_pk_add_f32 v[38:39], v[38:39], v[214:215]
	v_pk_add_f32 v[36:37], v[36:37], v[212:213]
	global_store_dwordx4 v237, v[36:39], s[4:5] offset:576
	s_waitcnt vmcnt(15)
	v_pk_add_f32 v[34:35], v[34:35], v[218:219]
	v_pk_add_f32 v[32:33], v[32:33], v[216:217]
	global_store_dwordx4 v238, v[32:35], s[4:5]
	s_waitcnt vmcnt(15)
	v_pk_add_f32 v[26:27], v[26:27], v[222:223]
	v_pk_add_f32 v[24:25], v[24:25], v[220:221]
	global_store_dwordx4 v238, v[24:27], s[4:5] offset:64
	s_waitcnt vmcnt(15)
	v_pk_add_f32 v[22:23], v[22:23], v[226:227]
	v_pk_add_f32 v[20:21], v[20:21], v[224:225]
	global_store_dwordx4 v238, v[20:23], s[4:5] offset:512
	s_waitcnt vmcnt(15)
	v_pk_add_f32 v[18:19], v[18:19], v[230:231]
	v_pk_add_f32 v[16:17], v[16:17], v[228:229]
	global_store_dwordx4 v238, v[16:19], s[4:5] offset:576
	s_waitcnt vmcnt(15)
	v_pk_add_f32 v[14:15], v[14:15], v[234:235]
	v_pk_add_f32 v[12:13], v[12:13], v[232:233]
	global_store_dwordx4 v239, v[12:15], s[4:5]
	s_waitcnt vmcnt(15)
	v_pk_add_f32 v[10:11], v[10:11], v[156:157]
	v_pk_add_f32 v[8:9], v[8:9], v[154:155]
	global_store_dwordx4 v239, v[8:11], s[4:5] offset:64
	s_waitcnt vmcnt(15)
	v_pk_add_f32 v[6:7], v[6:7], v[160:161]
	v_pk_add_f32 v[4:5], v[4:5], v[158:159]
	global_store_dwordx4 v239, v[4:7], s[4:5] offset:512
	s_waitcnt vmcnt(15)
	v_pk_add_f32 v[2:3], v[2:3], v[146:147]
	v_pk_add_f32 v[0:1], v[0:1], v[144:145]
	global_store_dwordx4 v239, v[0:3], s[4:5] offset:576
	s_mov_b32 s7, 0xb0000
	s_mov_b32 s52, s6
	s_mov_b32 s14, s8
	s_mov_b64 s[18:19], s[12:13]
	s_mov_b64 s[16:17], s[10:11]
	s_and_b64 vcc, exec, s[2:3]
	s_cbranch_vccz .LBB0_1890
	s_waitcnt vmcnt(0)
	s_cmpk_gt_u32 s0, 0xff
	s_cbranch_scc1 .LBB0_1901
	s_barrier
